# one static s_setprio 1 for waves 0-3 (leading half) per GEMM phase, all per-segment flips deleted
# speedup vs baseline: 1.0011x; 1.0011x over previous
; template <class Epi, class Sched, bool ABLK = false, bool ALIGN_EPI = true, bool SP2 = true, bool BBLK = true>
; __device__ __forceinline__ void gemm_phase(LAS unsigned char* lds, const Gemm g, const Sched& S, const Epi& E) {
;     const int tid = tid_fresh(), wid = __builtin_amdgcn_readfirstlane(tid >> 6), lane = tid & 63, wr = wid >> 2, wc = wid & 3, fr = lane & 15, fq = lane >> 4;
;     unsigned voffA[2], voffB[2];
; #pragma unroll
;     for (int i = 0; i < 2; ++i) { int R, C; stage_rc(tid * 16 + i * 8192, R, C); const int r32 = Epi::PERM ? perm32(R & 31) : (R & 31);
;         const int Rb = Epi::ADJ ? 64 * (R >> 5) + r32 : (R & ~31) + r32;
;         voffA[i] = (unsigned)(R * (ABLK ? 64 : g.lda) + C) * 2u; voffB[i] = BBLK ? (unsigned)(R * 64 + C) * 2u : (unsigned)(Rb * g.ldb + C) * 2u; }
;     const size_t kstep = (size_t)(BK * 2);
;     const size_t hstepA = (size_t)HALF * (ABLK ? 64 : g.lda) * 2, hstepB = BBLK ? (size_t)16384 : (size_t)(Epi::ADJ ? 32 : HALF) * g.ldb * 2;
;     const size_t tstepB = BBLK ? ((size_t)g.ldb / 64) * 32768 : (size_t)BM * g.ldb * 2;
;     const size_t kstepB = BBLK ? (size_t)32768 : kstep;
;     auto b_k0 = [&](int k0) -> size_t { return BBLK ? (size_t)(k0 / BK) * 32768 : (size_t)k0 * 2; };
;     const unsigned ldsw = (unsigned)wid * 1024u;
;     const int aoff = lds_byte(wr * 64 + fr, fq * 8), boff = lds_byte(wc * 32 + fr, fq * 8);
;     ...
;     Unit cur, nxt; int ui = 0;
;     if (!S.next(0, cur)) return;
;     f32x4 acc[2][2][4][2];
; #pragma unroll
;     for (int a = 0; a < 2; ++a)
; #pragma unroll
;         for (int b = 0; b < 2; ++b)
; #pragma unroll
;             for (int m = 0; m < 4; ++m)
; #pragma unroll
;                 for (int n = 0; n < 2; ++n) acc[a][b][m][n] = (f32x4){0.f, 0.f, 0.f, 0.f};
;     bf16x8 At[4][2], B0[2][2], B1[2][2];
;     auto a_unit = [&](const Unit& u) -> const char* { return ABLK ? (const char*)g.A + (size_t)u.pm * ((size_t)g.lda / 64) * 32768 : (const char*)g.A + (size_t)u.pm * 2 * hstepA; };
;     auto a_tile = [&](const char* ub, int tau) -> const char* { return ub + (size_t)tau * (ABLK ? (size_t)32768 : kstep); };
;     const char* uA = a_unit(cur); int tbA = cur.k0 / BK;
;     const char* cA = a_tile(uA, tbA); const char* cB = (const char*)g.Bt + (size_t)cur.pn * tstepB + b_k0(cur.k0);
;     S.a_ready(cur);
;     if constexpr (SP2) {
.LBB0_341:
	s_or_b64 exec, exec, s[2:3]
	s_add_u32 s16, s68, 0x1e100000
	s_addc_u32 s17, s69, 0
	s_and_b32 s91, s90, 7
	s_ashr_i32 s70, s90, 3
	s_cmpk_lt_i32 s70, 0x50
	s_waitcnt vmcnt(22)
	v_mov_b32_e32 v6, v0
	s_cselect_b64 s[0:1], -1, 0
	s_waitcnt lgkmcnt(0)
	s_barrier
	v_writelane_b32 v252, s0, 12
	s_cmpk_gt_i32 s70, 0x4f
	v_readfirstlane_b32 s4, v6
	v_writelane_b32 v252, s1, 13
	s_cbranch_scc1 .LBB0_357
	v_lshlrev_b32_e32 v1, 4, v6
	v_add_u32_e32 v2, 0x2000, v1
	v_ashrrev_i32_e32 v3, 31, v2
	v_lshrrev_b32_e32 v3, 22, v3
	v_add_u32_e32 v3, v2, v3
	v_ashrrev_i32_e32 v7, 10, v3
	v_mul_i32_i24_e32 v4, 0x400, v7
	v_sub_u32_e32 v2, v2, v4
	v_lshrrev_b32_e32 v4, 4, v2
	v_bitop3_b32 v2, v4, v2, 32 bitop3:0x6c
	v_ashrrev_i32_e32 v4, 31, v2
	v_lshrrev_b32_e32 v4, 26, v4
	v_add_u32_e32 v4, v2, v4
	v_ashrrev_i32_e32 v8, 6, v4
	v_and_b32_e32 v4, 0xc0, v4
	v_sub_u32_e32 v2, v2, v4
	v_mov_b32_e32 v4, 1
	v_lshlrev_b32_e32 v3, 5, v7
	v_ashrrev_i16_sdwa v2, v4, sext(v2) dst_sel:DWORD dst_unused:UNUSED_PAD src0_sel:DWORD src1_sel:BYTE_0
	v_and_b32_e32 v3, 32, v3
	v_bfe_i32 v9, v2, 0, 16
	v_add_u32_e32 v2, v3, v9
	v_lshlrev_b32_e32 v3, 3, v7
	v_and_b32_e32 v3, -16, v3
	v_add_u32_e32 v3, v8, v3
	v_lshlrev_b32_e32 v5, 7, v3
	v_lshl_add_u32 v130, v2, 1, v5
	s_movk_i32 s7, 0xf80
	v_mad_u64_u32 v[132:133], s[2:3], v3, s7, v[130:131]
	v_bfe_i32 v3, v6, 27, 1
	v_lshrrev_b32_e32 v3, 22, v3
	v_add_u32_e32 v3, v1, v3
	v_and_b32_e32 v3, 0xfffffc00, v3
	v_sub_u32_e32 v1, v1, v3
	v_lshrrev_b32_e32 v3, 4, v1
	v_bitop3_b32 v3, v3, v1, 32 bitop3:0x6c
	v_ashrrev_i32_e32 v1, 31, v1
	v_lshrrev_b32_e32 v1, 26, v1
	v_ashrrev_i32_e32 v2, 31, v6
	v_add_u32_e32 v1, v3, v1
	v_lshrrev_b32_e32 v2, 26, v2
	s_waitcnt vmcnt(21)
	v_ashrrev_i32_e32 v11, 6, v1
	v_add_u32_e32 v2, v6, v2
	v_mul_i32_i24_e32 v1, 64, v11
	v_ashrrev_i32_e32 v10, 6, v2
	v_sub_u32_e32 v1, v3, v1
	v_lshlrev_b32_e32 v2, 5, v10
	v_ashrrev_i16_sdwa v1, v4, sext(v1) dst_sel:DWORD dst_unused:UNUSED_PAD src0_sel:DWORD src1_sel:BYTE_0
	v_and_b32_e32 v2, 32, v2
	v_bfe_i32 v12, v1, 0, 16
	v_add_u32_e32 v1, v2, v12
	v_lshlrev_b32_e32 v2, 3, v10
	v_and_b32_e32 v2, -16, v2
	s_add_u32 s0, s68, 0x100000
	v_add_u32_e32 v2, v11, v2
	s_addc_u32 s1, s69, 0
	s_ashr_i32 s6, s4, 6
	v_lshlrev_b32_e32 v3, 7, v2
	s_ashr_i32 s5, s4, 8
	s_lshl_b32 s33, s6, 10
	v_lshl_add_u32 v134, v1, 1, v3
	s_add_u32 s36, s68, 0x2d100000
	v_mad_u64_u32 v[136:137], s[2:3], v2, s7, v[134:135]
	s_addc_u32 s37, s69, 0
	s_lshr_b32 s2, s70, 31
	s_add_i32 s2, s70, s2
	s_ashr_i32 s20, s2, 1
	s_sub_i32 s2, s91, s20
	s_lshl_b32 s2, s2, 1
	s_add_i32 s22, s2, s70
	s_ashr_i32 s21, s20, 31
	s_ashr_i32 s23, s22, 31
	s_lshl_b64 s[2:3], s[20:21], 20
	s_lshl_b64 s[8:9], s[22:23], 20
	s_add_u32 s26, s0, s8
	s_addc_u32 s27, s1, s9
	s_add_i32 s21, s33, 0
	s_add_i32 m0, s21, 0x10000
	v_mov_b32_e32 v135, 0
	global_load_lds_dwordx4 v134, s[26:27]
	s_add_i32 m0, s21, 0x12000
	s_add_u32 s8, s26, 0x4000
	global_load_lds_dwordx4 v130, s[26:27]
	s_addc_u32 s9, s27, 0
	s_add_i32 m0, s21, 0x14000
	v_mov_b32_e32 v137, v135
	global_load_lds_dwordx4 v134, s[8:9]
	s_add_i32 m0, s21, 0x16000
	s_add_u32 s24, s36, s2
	s_addc_u32 s25, s37, s3
	s_add_i32 s23, s21, 0x2000
	global_load_lds_dwordx4 v130, s[8:9]
	s_mov_b32 m0, s21
	s_add_u32 s2, s24, 0x80000
	global_load_lds_dwordx4 v136, s[24:25]
	s_mov_b32 m0, s23
	s_addc_u32 s3, s25, 0
	s_add_i32 s39, s21, 0x4000
	global_load_lds_dwordx4 v132, s[24:25]
	s_mov_b32 m0, s39
	s_add_i32 s40, s21, 0x6000
	global_load_lds_dwordx4 v136, s[2:3]
	s_mov_b32 m0, s40
	v_mov_b32_e32 v133, v135
	global_load_lds_dwordx4 v132, s[2:3]
	s_cmp_eq_u32 s5, 1
	s_mov_b32 s41, 0
	v_mov_b32_e32 v131, v135
	v_lshl_add_u64 v[2:3], s[24:25], 0, v[136:137]
	s_cselect_b64 s[2:3], -1, 0
	s_setprio 1
	s_cmp_lg_u32 s5, 1
	v_lshl_add_u64 v[4:5], s[24:25], 0, v[132:133]
	s_cbranch_scc1 .LBB0_344
	s_setprio 0
	s_barrier

; template <class Epi, class Sched, bool ABLK = false, bool ALIGN_EPI = true, bool SP2 = true, bool BBLK = true>
; __device__ __forceinline__ void gemm_phase(LAS unsigned char* lds, const Gemm g, const Sched& S, const Epi& E) {
;     const int tid = tid_fresh(), wid = __builtin_amdgcn_readfirstlane(tid >> 6), lane = tid & 63, wr = wid >> 2, wc = wid & 3, fr = lane & 15, fq = lane >> 4;
;     unsigned voffA[2], voffB[2];
; #pragma unroll
;     for (int i = 0; i < 2; ++i) { int R, C; stage_rc(tid * 16 + i * 8192, R, C); const int r32 = Epi::PERM ? perm32(R & 31) : (R & 31);
;         const int Rb = Epi::ADJ ? 64 * (R >> 5) + r32 : (R & ~31) + r32;
;         voffA[i] = (unsigned)(R * (ABLK ? 64 : g.lda) + C) * 2u; voffB[i] = BBLK ? (unsigned)(R * 64 + C) * 2u : (unsigned)(Rb * g.ldb + C) * 2u; }
;     const size_t kstep = (size_t)(BK * 2);
;     const size_t hstepA = (size_t)HALF * (ABLK ? 64 : g.lda) * 2, hstepB = BBLK ? (size_t)16384 : (size_t)(Epi::ADJ ? 32 : HALF) * g.ldb * 2;
;     const size_t tstepB = BBLK ? ((size_t)g.ldb / 64) * 32768 : (size_t)BM * g.ldb * 2;
;     const size_t kstepB = BBLK ? (size_t)32768 : kstep;
;     auto b_k0 = [&](int k0) -> size_t { return BBLK ? (size_t)(k0 / BK) * 32768 : (size_t)k0 * 2; };
;     const unsigned ldsw = (unsigned)wid * 1024u;
;     const int aoff = lds_byte(wr * 64 + fr, fq * 8), boff = lds_byte(wc * 32 + fr, fq * 8);
;     ...
;     Unit cur, nxt; int ui = 0;
;     if (!S.next(0, cur)) return;
;     f32x4 acc[2][2][4][2];
; #pragma unroll
;     for (int a = 0; a < 2; ++a)
; #pragma unroll
;         for (int b = 0; b < 2; ++b)
; #pragma unroll
;             for (int m = 0; m < 4; ++m)
; #pragma unroll
;                 for (int n = 0; n < 2; ++n) acc[a][b][m][n] = (f32x4){0.f, 0.f, 0.f, 0.f};
;     bf16x8 At[4][2], B0[2][2], B1[2][2];
;     auto a_unit = [&](const Unit& u) -> const char* { return ABLK ? (const char*)g.A + (size_t)u.pm * ((size_t)g.lda / 64) * 32768 : (const char*)g.A + (size_t)u.pm * 2 * hstepA; };
;     auto a_tile = [&](const char* ub, int tau) -> const char* { return ub + (size_t)tau * (ABLK ? (size_t)32768 : kstep); };
;     const char* uA = a_unit(cur); int tbA = cur.k0 / BK;
;     const char* cA = a_tile(uA, tbA); const char* cB = (const char*)g.Bt + (size_t)cur.pn * tstepB + b_k0(cur.k0);
;     S.a_ready(cur);
;     if constexpr (SP2) {
.LBB0_466:
	s_or_b64 exec, exec, s[2:3]
	s_add_u32 s1, s68, 0x23100000
	s_addc_u32 s33, s69, 0
	s_cmpk_lt_i32 s70, 0xa0
	s_waitcnt lgkmcnt(0)
	v_mov_b32_e32 v1, v0
	s_cselect_b64 s[2:3], -1, 0
	s_barrier
	v_writelane_b32 v252, s2, 14
	s_cmpk_gt_i32 s70, 0x9f
	v_readfirstlane_b32 s6, v1
	v_writelane_b32 v252, s3, 15
	s_cbranch_scc1 .LBB0_482
	v_lshlrev_b32_e32 v2, 4, v1
	v_add_u32_e32 v3, 0x2000, v2
	v_ashrrev_i32_e32 v4, 31, v3
	v_lshrrev_b32_e32 v4, 22, v4
	v_add_u32_e32 v4, v3, v4
	v_ashrrev_i32_e32 v6, 10, v4
	v_mul_i32_i24_e32 v5, 0x400, v6
	v_sub_u32_e32 v3, v3, v5
	v_lshrrev_b32_e32 v5, 4, v3
	v_bitop3_b32 v3, v5, v3, 32 bitop3:0x6c
	v_ashrrev_i32_e32 v5, 31, v3
	v_lshrrev_b32_e32 v5, 26, v5
	v_add_u32_e32 v5, v3, v5
	v_ashrrev_i32_e32 v7, 6, v5
	v_and_b32_e32 v5, 0xc0, v5
	v_sub_u32_e32 v3, v3, v5
	v_mov_b32_e32 v5, 1
	v_lshlrev_b32_e32 v4, 5, v6
	v_ashrrev_i16_sdwa v3, v5, sext(v3) dst_sel:DWORD dst_unused:UNUSED_PAD src0_sel:DWORD src1_sel:BYTE_0
	v_and_b32_e32 v4, 32, v4
	v_bfe_i32 v8, v3, 0, 16
	v_add_u32_e32 v3, v4, v8
	v_lshlrev_b32_e32 v4, 3, v6
	v_and_b32_e32 v4, -16, v4
	v_add_u32_e32 v4, v7, v4
	v_lshlrev_b32_e32 v9, 7, v4
	v_lshl_add_u32 v130, v3, 1, v9
	s_movk_i32 s4, 0xf80
	v_mad_u64_u32 v[132:133], s[2:3], v4, s4, v[130:131]
	v_bfe_i32 v4, v1, 27, 1
	v_lshrrev_b32_e32 v4, 22, v4
	v_add_u32_e32 v4, v2, v4
	v_and_b32_e32 v4, 0xfffffc00, v4
	v_sub_u32_e32 v2, v2, v4
	v_lshrrev_b32_e32 v4, 4, v2
	v_bitop3_b32 v4, v4, v2, 32 bitop3:0x6c
	v_ashrrev_i32_e32 v2, 31, v2
	v_lshrrev_b32_e32 v2, 26, v2
	v_ashrrev_i32_e32 v3, 31, v1
	v_add_u32_e32 v2, v4, v2
	v_lshrrev_b32_e32 v3, 26, v3
	v_ashrrev_i32_e32 v10, 6, v2
	v_add_u32_e32 v3, v1, v3
	v_mul_i32_i24_e32 v2, 64, v10
	v_ashrrev_i32_e32 v9, 6, v3
	v_sub_u32_e32 v2, v4, v2
	v_lshlrev_b32_e32 v3, 5, v9
	v_ashrrev_i16_sdwa v2, v5, sext(v2) dst_sel:DWORD dst_unused:UNUSED_PAD src0_sel:DWORD src1_sel:BYTE_0
	v_and_b32_e32 v3, 32, v3
	v_bfe_i32 v11, v2, 0, 16
	v_add_u32_e32 v2, v3, v11
	v_lshlrev_b32_e32 v3, 3, v9
	v_and_b32_e32 v3, -16, v3
	s_add_u32 s0, s68, 0x6900000
	v_add_u32_e32 v3, v10, v3
	s_addc_u32 s39, s69, 0
	s_ashr_i32 s8, s6, 6
	v_lshlrev_b32_e32 v4, 7, v3
	s_ashr_i32 s7, s6, 8
	s_lshl_b32 s40, s8, 10
	v_lshl_add_u32 v134, v2, 1, v4
	s_add_u32 s41, s68, 0x1b900000
	v_mad_u64_u32 v[136:137], s[2:3], v3, s4, v[134:135]
	s_addc_u32 s42, s69, 0
	s_lshr_b32 s2, s70, 30
	s_add_i32 s2, s70, s2
	s_ashr_i32 s22, s2, 2
	s_sub_i32 s2, s91, s22
	s_lshl_b32 s2, s2, 2
	s_add_i32 s24, s2, s70
	s_ashr_i32 s23, s22, 31
	s_ashr_i32 s25, s24, 31
	s_lshl_b64 s[2:3], s[22:23], 20
	s_lshl_b64 s[4:5], s[24:25], 20
	s_add_u32 s28, s0, s4
	s_addc_u32 s29, s39, s5
	s_add_i32 s25, s40, 0
	s_add_i32 m0, s25, 0x10000
	v_mov_b32_e32 v139, 0
	global_load_lds_dwordx4 v134, s[28:29]
	s_add_i32 m0, s25, 0x12000
	s_add_u32 s4, s28, 0x4000
	global_load_lds_dwordx4 v130, s[28:29]
	s_addc_u32 s5, s29, 0
	s_add_i32 m0, s25, 0x14000
	v_mov_b32_e32 v137, v139
	global_load_lds_dwordx4 v134, s[4:5]
	s_add_i32 m0, s25, 0x16000
	s_add_u32 s26, s41, s2
	s_addc_u32 s27, s42, s3
	s_add_i32 s43, s25, 0x2000
	global_load_lds_dwordx4 v130, s[4:5]
	s_mov_b32 m0, s25
	s_add_u32 s2, s26, 0x80000
	global_load_lds_dwordx4 v136, s[26:27]
	s_mov_b32 m0, s43
	s_addc_u32 s3, s27, 0
	s_add_i32 s46, s25, 0x4000
	global_load_lds_dwordx4 v132, s[26:27]
	s_mov_b32 m0, s46
	s_add_i32 s47, s25, 0x6000
	global_load_lds_dwordx4 v136, s[2:3]
	s_mov_b32 m0, s47
	v_mov_b32_e32 v133, v139
	global_load_lds_dwordx4 v132, s[2:3]
	s_cmp_eq_u32 s7, 1
	s_mov_b32 s48, 0
	v_mov_b32_e32 v135, v139
	v_mov_b32_e32 v131, v139
	s_mov_b64 s[4:5], 0x4000
	v_lshl_add_u64 v[2:3], s[26:27], 0, v[136:137]
	s_cselect_b64 s[2:3], -1, 0
	s_setprio 1
	s_cmp_lg_u32 s7, 1
	v_lshl_add_u64 v[4:5], s[26:27], 0, v[132:133]
	s_cbranch_scc1 .LBB0_469
	s_setprio 0
	s_barrier

; template <class Epi, class Sched, bool ABLK = false, bool ALIGN_EPI = true, bool SP2 = true, bool BBLK = true>
; __device__ __forceinline__ void gemm_phase(LAS unsigned char* lds, const Gemm g, const Sched& S, const Epi& E) {
;     const int tid = tid_fresh(), wid = __builtin_amdgcn_readfirstlane(tid >> 6), lane = tid & 63, wr = wid >> 2, wc = wid & 3, fr = lane & 15, fq = lane >> 4;
;     unsigned voffA[2], voffB[2];
; #pragma unroll
;     for (int i = 0; i < 2; ++i) { int R, C; stage_rc(tid * 16 + i * 8192, R, C); const int r32 = Epi::PERM ? perm32(R & 31) : (R & 31);
;         const int Rb = Epi::ADJ ? 64 * (R >> 5) + r32 : (R & ~31) + r32;
;         voffA[i] = (unsigned)(R * (ABLK ? 64 : g.lda) + C) * 2u; voffB[i] = BBLK ? (unsigned)(R * 64 + C) * 2u : (unsigned)(Rb * g.ldb + C) * 2u; }
;     const size_t kstep = (size_t)(BK * 2);
;     const size_t hstepA = (size_t)HALF * (ABLK ? 64 : g.lda) * 2, hstepB = BBLK ? (size_t)16384 : (size_t)(Epi::ADJ ? 32 : HALF) * g.ldb * 2;
;     const size_t tstepB = BBLK ? ((size_t)g.ldb / 64) * 32768 : (size_t)BM * g.ldb * 2;
;     const size_t kstepB = BBLK ? (size_t)32768 : kstep;
;     auto b_k0 = [&](int k0) -> size_t { return BBLK ? (size_t)(k0 / BK) * 32768 : (size_t)k0 * 2; };
;     const unsigned ldsw = (unsigned)wid * 1024u;
;     const int aoff = lds_byte(wr * 64 + fr, fq * 8), boff = lds_byte(wc * 32 + fr, fq * 8);
;     ...
;     Unit cur, nxt; int ui = 0;
;     if (!S.next(0, cur)) return;
;     f32x4 acc[2][2][4][2];
; #pragma unroll
;     for (int a = 0; a < 2; ++a)
; #pragma unroll
;         for (int b = 0; b < 2; ++b)
; #pragma unroll
;             for (int m = 0; m < 4; ++m)
; #pragma unroll
;                 for (int n = 0; n < 2; ++n) acc[a][b][m][n] = (f32x4){0.f, 0.f, 0.f, 0.f};
;     bf16x8 At[4][2], B0[2][2], B1[2][2];
;     auto a_unit = [&](const Unit& u) -> const char* { return ABLK ? (const char*)g.A + (size_t)u.pm * ((size_t)g.lda / 64) * 32768 : (const char*)g.A + (size_t)u.pm * 2 * hstepA; };
;     auto a_tile = [&](const char* ub, int tau) -> const char* { return ub + (size_t)tau * (ABLK ? (size_t)32768 : kstep); };
;     const char* uA = a_unit(cur); int tbA = cur.k0 / BK;
;     const char* cA = a_tile(uA, tbA); const char* cB = (const char*)g.Bt + (size_t)cur.pn * tstepB + b_k0(cur.k0);
;     S.a_ready(cur);
;     if constexpr (SP2) {
.LBB0_534:
	s_or_b64 exec, exec, s[2:3]
	v_mov_b32_e32 v6, v0
	s_waitcnt lgkmcnt(0)
	s_barrier
	s_add_u32 s39, s68, 0xe900000
	v_bfe_i32 v3, v6, 27, 1
	v_lshlrev_b32_e32 v1, 4, v6
	v_lshrrev_b32_e32 v3, 22, v3
	v_add_u32_e32 v3, v1, v3
	v_and_b32_e32 v3, 0xfffffc00, v3
	v_sub_u32_e32 v3, v1, v3
	v_lshrrev_b32_e32 v4, 4, v3
	v_bitop3_b32 v4, v4, v3, 32 bitop3:0x6c
	v_ashrrev_i32_e32 v3, 31, v3
	v_lshrrev_b32_e32 v3, 26, v3
	v_ashrrev_i32_e32 v2, 31, v6
	v_add_u32_e32 v3, v4, v3
	v_lshrrev_b32_e32 v2, 26, v2
	v_ashrrev_i32_e32 v3, 6, v3
	v_add_u32_e32 v2, v6, v2
	v_mul_i32_i24_e32 v8, 64, v3
	v_ashrrev_i32_e32 v2, 6, v2
	v_sub_u32_e32 v4, v4, v8
	v_mov_b32_e32 v8, 1
	v_lshlrev_b32_e32 v5, 3, v2
	v_lshlrev_b32_e32 v7, 5, v2
	v_ashrrev_i16_sdwa v4, v8, sext(v4) dst_sel:DWORD dst_unused:UNUSED_PAD src0_sel:DWORD src1_sel:BYTE_0
	v_and_b32_e32 v5, 0x1fffff0, v5
	v_and_b32_e32 v7, 32, v7
	v_bfe_i32 v4, v4, 0, 16
	v_add_u32_e32 v7, v7, v4
	v_add_lshl_u32 v5, v3, v5, 7
	v_add_u32_e32 v1, 0x2000, v1
	v_lshl_add_u32 v130, v7, 1, v5
	v_ashrrev_i32_e32 v5, 31, v1
	v_lshrrev_b32_e32 v5, 22, v5
	v_add_u32_e32 v5, v1, v5
	v_ashrrev_i32_e32 v5, 10, v5
	v_mul_i32_i24_e32 v7, 0x400, v5
	v_sub_u32_e32 v1, v1, v7
	v_lshrrev_b32_e32 v7, 4, v1
	v_bitop3_b32 v1, v7, v1, 32 bitop3:0x6c
	v_lshlrev_b32_e32 v7, 3, v5
	s_addc_u32 s50, s69, 0
	v_and_b32_e32 v9, 0x1fffff0, v7
	v_ashrrev_i32_e32 v7, 31, v1
	s_lshl_b32 s2, s91, 2
	s_ashr_i32 s3, s90, 6
	v_readfirstlane_b32 s0, v6
	v_lshrrev_b32_e32 v7, 26, v7
	s_add_i32 s82, s2, s3
	s_ashr_i32 s5, s0, 6
	v_add_u32_e32 v10, v1, v7
	s_bfe_u32 s78, s90, 0x30003
	s_ashr_i32 s83, s82, 31
	v_ashrrev_i32_e32 v7, 6, v10
	v_and_b32_e32 v10, 0xc0, v10
	s_ashr_i32 s4, s0, 8
	s_lshl_b32 s51, s5, 10
	s_lshl_b64 s[6:7], s[82:83], 22
	s_lshl_b32 s2, s78, 22
	v_sub_u32_e32 v1, v1, v10
	s_add_u32 s40, s39, s2
	v_lshlrev_b32_e32 v11, 5, v5
	v_ashrrev_i16_sdwa v1, v8, sext(v1) dst_sel:DWORD dst_unused:UNUSED_PAD src0_sel:DWORD src1_sel:BYTE_0
	s_addc_u32 s41, s50, 0
	s_add_i32 s52, s51, 0
	v_and_b32_e32 v11, 32, v11
	v_bfe_i32 v8, v1, 0, 16
	s_add_i32 m0, s52, 0x10000
	v_add_u32_e32 v1, v11, v8
	v_add_lshl_u32 v9, v7, v9, 7
	global_load_lds_dwordx4 v130, s[40:41]
	s_add_i32 m0, s52, 0x12000
	v_lshl_add_u32 v132, v1, 1, v9
	v_writelane_b32 v252, s2, 16
	s_add_u32 s2, s40, 0x4000
	global_load_lds_dwordx4 v132, s[40:41]
	s_addc_u32 s3, s41, 0
	s_add_i32 m0, s52, 0x14000
	v_mov_b32_e32 v131, 0
	global_load_lds_dwordx4 v130, s[2:3]
	s_add_i32 m0, s52, 0x16000
	s_add_u32 s42, s1, s6
	v_writelane_b32 v252, s6, 17
	s_addc_u32 s43, s33, s7
	s_add_i32 s53, s52, 0x2000
	global_load_lds_dwordx4 v132, s[2:3]
	s_mov_b32 m0, s52
	s_add_u32 s2, s42, 0x4000
	global_load_lds_dwordx4 v130, s[42:43]
	s_mov_b32 m0, s53
	s_addc_u32 s3, s43, 0
	s_add_i32 s54, s52, 0x4000
	global_load_lds_dwordx4 v132, s[42:43]
	s_mov_b32 m0, s54
	s_add_i32 s55, s52, 0x6000
	global_load_lds_dwordx4 v130, s[2:3]
	s_mov_b32 m0, s55
	s_cmp_eq_u32 s4, 1
	global_load_lds_dwordx4 v132, s[2:3]
	s_mov_b32 s58, 0
	s_cselect_b64 s[2:3], -1, 0
	s_setprio 1
	s_cmp_lg_u32 s4, 1
	v_mov_b32_e32 v133, v131
	v_writelane_b32 v252, s7, 18
	s_cbranch_scc1 .LBB0_536
	s_setprio 0
	s_barrier

; template <class Epi, class Sched, bool ABLK = false, bool ALIGN_EPI = true, bool SP2 = true, bool BBLK = true>
; __device__ __forceinline__ void gemm_phase(LAS unsigned char* lds, const Gemm g, const Sched& S, const Epi& E) {
;     const int tid = tid_fresh(), wid = __builtin_amdgcn_readfirstlane(tid >> 6), lane = tid & 63, wr = wid >> 2, wc = wid & 3, fr = lane & 15, fq = lane >> 4;
;     unsigned voffA[2], voffB[2];
; #pragma unroll
;     for (int i = 0; i < 2; ++i) { int R, C; stage_rc(tid * 16 + i * 8192, R, C); const int r32 = Epi::PERM ? perm32(R & 31) : (R & 31);
;         const int Rb = Epi::ADJ ? 64 * (R >> 5) + r32 : (R & ~31) + r32;
;         voffA[i] = (unsigned)(R * (ABLK ? 64 : g.lda) + C) * 2u; voffB[i] = BBLK ? (unsigned)(R * 64 + C) * 2u : (unsigned)(Rb * g.ldb + C) * 2u; }
;     const size_t kstep = (size_t)(BK * 2);
;     const size_t hstepA = (size_t)HALF * (ABLK ? 64 : g.lda) * 2, hstepB = BBLK ? (size_t)16384 : (size_t)(Epi::ADJ ? 32 : HALF) * g.ldb * 2;
;     const size_t tstepB = BBLK ? ((size_t)g.ldb / 64) * 32768 : (size_t)BM * g.ldb * 2;
;     const size_t kstepB = BBLK ? (size_t)32768 : kstep;
;     auto b_k0 = [&](int k0) -> size_t { return BBLK ? (size_t)(k0 / BK) * 32768 : (size_t)k0 * 2; };
;     const unsigned ldsw = (unsigned)wid * 1024u;
;     const int aoff = lds_byte(wr * 64 + fr, fq * 8), boff = lds_byte(wc * 32 + fr, fq * 8);
;     ...
;     Unit cur, nxt; int ui = 0;
;     if (!S.next(0, cur)) return;
;     f32x4 acc[2][2][4][2];
; #pragma unroll
;     for (int a = 0; a < 2; ++a)
; #pragma unroll
;         for (int b = 0; b < 2; ++b)
; #pragma unroll
;             for (int m = 0; m < 4; ++m)
; #pragma unroll
;                 for (int n = 0; n < 2; ++n) acc[a][b][m][n] = (f32x4){0.f, 0.f, 0.f, 0.f};
;     bf16x8 At[4][2], B0[2][2], B1[2][2];
;     auto a_unit = [&](const Unit& u) -> const char* { return ABLK ? (const char*)g.A + (size_t)u.pm * ((size_t)g.lda / 64) * 32768 : (const char*)g.A + (size_t)u.pm * 2 * hstepA; };
;     auto a_tile = [&](const char* ub, int tau) -> const char* { return ub + (size_t)tau * (ABLK ? (size_t)32768 : kstep); };
;     const char* uA = a_unit(cur); int tbA = cur.k0 / BK;
;     const char* cA = a_tile(uA, tbA); const char* cB = (const char*)g.Bt + (size_t)cur.pn * tstepB + b_k0(cur.k0);
;     S.a_ready(cur);
;     if constexpr (SP2) {
.LBB0_659:
	s_load_dwordx4 s[12:15], s[86:87], 0xf0
	s_waitcnt lgkmcnt(0)
	s_add_u32 s59, s14, 0x1b900000
	s_addc_u32 s62, s15, 0
	s_add_u32 s1, s14, 0x23100000
	s_addc_u32 s33, s15, 0
	s_andn2_b64 vcc, exec, s[2:3]
	s_cbranch_vccnz .LBB0_712
	v_ashrrev_i32_e32 v3, 31, v1
	v_lshrrev_b32_e32 v3, 26, v3
	v_add_u32_e32 v3, v1, v3
	v_ashrrev_i32_e32 v6, 6, v3
	v_bfe_i32 v3, v1, 27, 1
	v_lshlrev_b32_e32 v2, 4, v1
	v_lshrrev_b32_e32 v3, 22, v3
	v_add_u32_e32 v3, v2, v3
	v_and_b32_e32 v3, 0xfffffc00, v3
	v_sub_u32_e32 v3, v2, v3
	v_lshrrev_b32_e32 v4, 4, v3
	v_bitop3_b32 v4, v4, v3, 32 bitop3:0x6c
	v_ashrrev_i32_e32 v3, 31, v3
	v_lshrrev_b32_e32 v3, 26, v3
	v_add_u32_e32 v3, v4, v3
	v_ashrrev_i32_e32 v7, 6, v3
	v_lshlrev_b32_e32 v5, 3, v6
	v_mul_i32_i24_e32 v8, 64, v7
	v_and_b32_e32 v5, -16, v5
	v_sub_u32_e32 v4, v4, v8
	v_mov_b32_e32 v11, 1
	v_add_u32_e32 v3, v7, v5
	v_lshlrev_b32_e32 v5, 5, v6
	v_ashrrev_i16_sdwa v4, v11, sext(v4) dst_sel:DWORD dst_unused:UNUSED_PAD src0_sel:DWORD src1_sel:BYTE_0
	v_and_b32_e32 v5, 32, v5
	v_bfe_i32 v8, v4, 0, 16
	v_add_u32_e32 v4, v5, v8
	v_lshlrev_b32_e32 v5, 12, v3
	v_lshl_add_u32 v130, v4, 1, v5
	s_movk_i32 s3, 0xf080
	v_add_u32_e32 v2, 0x2000, v2
	v_mad_u64_u32 v[132:133], s[6:7], v3, s3, v[130:131]
	v_ashrrev_i32_e32 v3, 31, v2
	v_lshrrev_b32_e32 v3, 22, v3
	v_add_u32_e32 v3, v2, v3
	v_ashrrev_i32_e32 v9, 10, v3
	v_mul_i32_i24_e32 v3, 0x400, v9
	v_sub_u32_e32 v2, v2, v3
	v_lshrrev_b32_e32 v3, 4, v2
	v_bitop3_b32 v2, v3, v2, 32 bitop3:0x6c
	v_ashrrev_i32_e32 v4, 31, v2
	v_lshrrev_b32_e32 v4, 26, v4
	v_add_u32_e32 v4, v2, v4
	s_load_dwordx4 s[12:15], s[86:87], 0xf0
	v_ashrrev_i32_e32 v10, 6, v4
	v_and_b32_e32 v4, 0xc0, v4
	v_lshlrev_b32_e32 v3, 3, v9
	v_sub_u32_e32 v2, v2, v4
	v_and_b32_e32 v3, -16, v3
	v_lshlrev_b32_e32 v5, 5, v9
	v_ashrrev_i16_sdwa v2, v11, sext(v2) dst_sel:DWORD dst_unused:UNUSED_PAD src0_sel:DWORD src1_sel:BYTE_0
	v_add_u32_e32 v3, v10, v3
	v_and_b32_e32 v5, 32, v5
	v_bfe_i32 v11, v2, 0, 16
	v_add_u32_e32 v2, v5, v11
	v_lshlrev_b32_e32 v4, 12, v3
	s_waitcnt lgkmcnt(0)
	s_add_u32 s39, s14, 0x2100000
	v_lshl_add_u32 v134, v2, 1, v4
	s_addc_u32 s40, s15, 0
	s_ashr_i32 s2, s4, 6
	v_mad_u64_u32 v[136:137], s[6:7], v3, s3, v[134:135]
	s_ashr_i32 s25, s24, 31
	s_ashr_i32 s9, s8, 31
	s_ashr_i32 s5, s4, 8
	s_lshl_b32 s41, s2, 10
	s_lshl_b64 s[6:7], s[24:25], 20
	s_lshl_b64 s[10:11], s[8:9], 20
	s_add_u32 s28, s39, s10
	s_addc_u32 s29, s40, s11
	s_add_i32 s25, s41, 0
	s_add_i32 m0, s25, 0x10000
	v_mov_b32_e32 v139, 0
	global_load_lds_dwordx4 v132, s[28:29]
	s_add_i32 m0, s25, 0x12000
	s_add_u32 s10, s28, 0x4000
	global_load_lds_dwordx4 v136, s[28:29]
	s_addc_u32 s11, s29, 0
	s_add_i32 m0, s25, 0x14000
	v_mov_b32_e32 v131, v139
	global_load_lds_dwordx4 v132, s[10:11]
	s_add_i32 m0, s25, 0x16000
	s_add_u32 s26, s59, s6
	s_addc_u32 s27, s62, s7
	s_add_i32 s42, s25, 0x2000
	global_load_lds_dwordx4 v136, s[10:11]
	s_mov_b32 m0, s25
	s_add_u32 s6, s26, 0x80000
	global_load_lds_dwordx4 v130, s[26:27]
	s_mov_b32 m0, s42
	s_addc_u32 s7, s27, 0
	s_add_i32 s43, s25, 0x4000
	global_load_lds_dwordx4 v134, s[26:27]
	s_mov_b32 m0, s43
	s_add_i32 s46, s25, 0x6000
	global_load_lds_dwordx4 v130, s[6:7]
	s_mov_b32 m0, s46
	v_mov_b32_e32 v135, v139
	global_load_lds_dwordx4 v134, s[6:7]
	s_cmp_eq_u32 s5, 1
	s_mov_b32 s3, 0
	v_mov_b32_e32 v133, v139
	v_mov_b32_e32 v137, v139
	v_lshl_add_u64 v[2:3], s[26:27], 0, v[130:131]
	s_cselect_b64 s[10:11], -1, 0
	s_setprio 1
	s_cmp_lg_u32 s5, 1
	v_lshl_add_u64 v[4:5], s[26:27], 0, v[134:135]
	s_cbranch_scc1 .LBB0_662
	s_setprio 0
	s_barrier

; template <class Epi, class Sched, bool ABLK = false, bool ALIGN_EPI = true, bool SP2 = true, bool BBLK = true>
; __device__ __forceinline__ void gemm_phase(LAS unsigned char* lds, const Gemm g, const Sched& S, const Epi& E) {
;     const int tid = tid_fresh(), wid = __builtin_amdgcn_readfirstlane(tid >> 6), lane = tid & 63, wr = wid >> 2, wc = wid & 3, fr = lane & 15, fq = lane >> 4;
;     unsigned voffA[2], voffB[2];
; #pragma unroll
;     for (int i = 0; i < 2; ++i) { int R, C; stage_rc(tid * 16 + i * 8192, R, C); const int r32 = Epi::PERM ? perm32(R & 31) : (R & 31);
;         const int Rb = Epi::ADJ ? 64 * (R >> 5) + r32 : (R & ~31) + r32;
;         voffA[i] = (unsigned)(R * (ABLK ? 64 : g.lda) + C) * 2u; voffB[i] = BBLK ? (unsigned)(R * 64 + C) * 2u : (unsigned)(Rb * g.ldb + C) * 2u; }
;     const size_t kstep = (size_t)(BK * 2);
;     const size_t hstepA = (size_t)HALF * (ABLK ? 64 : g.lda) * 2, hstepB = BBLK ? (size_t)16384 : (size_t)(Epi::ADJ ? 32 : HALF) * g.ldb * 2;
;     const size_t tstepB = BBLK ? ((size_t)g.ldb / 64) * 32768 : (size_t)BM * g.ldb * 2;
;     const size_t kstepB = BBLK ? (size_t)32768 : kstep;
;     auto b_k0 = [&](int k0) -> size_t { return BBLK ? (size_t)(k0 / BK) * 32768 : (size_t)k0 * 2; };
;     const unsigned ldsw = (unsigned)wid * 1024u;
;     const int aoff = lds_byte(wr * 64 + fr, fq * 8), boff = lds_byte(wc * 32 + fr, fq * 8);
;     ...
;     Unit cur, nxt; int ui = 0;
;     if (!S.next(0, cur)) return;
;     f32x4 acc[2][2][4][2];
; #pragma unroll
;     for (int a = 0; a < 2; ++a)
; #pragma unroll
;         for (int b = 0; b < 2; ++b)
; #pragma unroll
;             for (int m = 0; m < 4; ++m)
; #pragma unroll
;                 for (int n = 0; n < 2; ++n) acc[a][b][m][n] = (f32x4){0.f, 0.f, 0.f, 0.f};
;     bf16x8 At[4][2], B0[2][2], B1[2][2];
;     auto a_unit = [&](const Unit& u) -> const char* { return ABLK ? (const char*)g.A + (size_t)u.pm * ((size_t)g.lda / 64) * 32768 : (const char*)g.A + (size_t)u.pm * 2 * hstepA; };
;     auto a_tile = [&](const char* ub, int tau) -> const char* { return ub + (size_t)tau * (ABLK ? (size_t)32768 : kstep); };
;     const char* uA = a_unit(cur); int tbA = cur.k0 / BK;
;     const char* cA = a_tile(uA, tbA); const char* cB = (const char*)g.Bt + (size_t)cur.pn * tstepB + b_k0(cur.k0);
;     S.a_ready(cur);
;     if constexpr (SP2) {
.LBB0_1032:
	s_or_b64 exec, exec, s[2:3]
	s_waitcnt vmcnt(7)
	v_mov_b32_e32 v8, v0
	s_waitcnt lgkmcnt(0)
	s_barrier
	v_readlane_b32 s4, v252, 19
	v_ashrrev_i32_e32 v3, 31, v8
	v_lshrrev_b32_e32 v3, 26, v3
	v_add_u32_e32 v3, v8, v3
	v_ashrrev_i32_e32 v6, 6, v3
	v_bfe_i32 v3, v8, 27, 1
	v_lshlrev_b32_e32 v2, 4, v8
	v_lshrrev_b32_e32 v3, 22, v3
	v_add_u32_e32 v3, v2, v3
	v_and_b32_e32 v3, 0xfffffc00, v3
	v_sub_u32_e32 v3, v2, v3
	v_lshrrev_b32_e32 v4, 4, v3
	v_bitop3_b32 v4, v4, v3, 32 bitop3:0x6c
	v_ashrrev_i32_e32 v3, 31, v3
	v_lshrrev_b32_e32 v3, 26, v3
	v_add_u32_e32 v3, v4, v3
	v_ashrrev_i32_e32 v7, 6, v3
	v_lshlrev_b32_e32 v5, 3, v6
	v_mul_i32_i24_e32 v9, 64, v7
	v_and_b32_e32 v5, -16, v5
	v_sub_u32_e32 v4, v4, v9
	s_waitcnt vmcnt(6)
	v_mov_b32_e32 v12, 1
	v_readlane_b32 s6, v252, 21
	v_add_u32_e32 v3, v7, v5
	v_lshlrev_b32_e32 v5, 5, v6
	v_ashrrev_i16_sdwa v4, v12, sext(v4) dst_sel:DWORD dst_unused:UNUSED_PAD src0_sel:DWORD src1_sel:BYTE_0
	v_readlane_b32 s7, v252, 22
	s_add_u32 s28, s6, 0x2d100000
	v_and_b32_e32 v5, 32, v5
	v_bfe_i32 v9, v4, 0, 16
	s_addc_u32 s29, s7, 0
	v_add_u32_e32 v4, v5, v9
	v_lshlrev_b32_e32 v5, 12, v3
	s_add_u32 s30, s6, 0x3900000
	v_lshl_add_u32 v130, v4, 1, v5
	s_movk_i32 s6, 0xf080
	v_add_u32_e32 v2, 0x2000, v2
	v_mad_u64_u32 v[132:133], s[2:3], v3, s6, v[130:131]
	v_ashrrev_i32_e32 v3, 31, v2
	v_lshrrev_b32_e32 v3, 22, v3
	v_add_u32_e32 v3, v2, v3
	v_ashrrev_i32_e32 v10, 10, v3
	v_mul_i32_i24_e32 v3, 0x400, v10
	v_sub_u32_e32 v2, v2, v3
	v_lshrrev_b32_e32 v3, 4, v2
	v_bitop3_b32 v2, v3, v2, 32 bitop3:0x6c
	v_ashrrev_i32_e32 v4, 31, v2
	v_lshrrev_b32_e32 v4, 26, v4
	v_add_u32_e32 v4, v2, v4
	v_ashrrev_i32_e32 v11, 6, v4
	v_and_b32_e32 v4, 0xc0, v4
	v_lshlrev_b32_e32 v3, 3, v10
	v_sub_u32_e32 v2, v2, v4
	v_and_b32_e32 v3, -16, v3
	v_lshlrev_b32_e32 v5, 5, v10
	v_ashrrev_i16_sdwa v2, v12, sext(v2) dst_sel:DWORD dst_unused:UNUSED_PAD src0_sel:DWORD src1_sel:BYTE_0
	v_add_u32_e32 v3, v11, v3
	v_and_b32_e32 v5, 32, v5
	v_bfe_i32 v12, v2, 0, 16
	v_readlane_b32 s5, v252, 20
	v_readfirstlane_b32 s4, v8
	v_add_u32_e32 v2, v5, v12
	v_lshlrev_b32_e32 v4, 12, v3
	s_addc_u32 s31, s7, 0
	s_ashr_i32 s5, s4, 6
	v_lshl_add_u32 v134, v2, 1, v4
	v_mad_u64_u32 v[136:137], s[2:3], v3, s6, v[134:135]
	s_ashr_i32 s6, s4, 8
	s_lshl_b32 s34, s5, 10
	s_lshl_b64 s[8:9], s[82:83], 20
	s_lshl_b32 s97, s78, 20
	s_add_u32 s20, s30, s97
	s_addc_u32 s21, s31, 0
	s_add_i32 s35, s34, 0
	s_add_i32 m0, s35, 0x10000
	v_mov_b32_e32 v133, 0
	global_load_lds_dwordx4 v132, s[20:21]
	s_add_i32 m0, s35, 0x12000
	s_add_u32 s2, s20, 0x4000
	global_load_lds_dwordx4 v136, s[20:21]
	s_addc_u32 s3, s21, 0
	s_add_i32 m0, s35, 0x14000
	v_mov_b32_e32 v131, v133
	global_load_lds_dwordx4 v132, s[2:3]
	s_add_i32 m0, s35, 0x16000
	s_add_u32 s22, s28, s8
	v_writelane_b32 v252, s8, 24
	s_addc_u32 s23, s29, s9
	s_add_i32 s36, s35, 0x2000
	global_load_lds_dwordx4 v136, s[2:3]
	s_mov_b32 m0, s35
	s_add_u32 s2, s22, 0x80000
	global_load_lds_dwordx4 v130, s[22:23]
	s_mov_b32 m0, s36
	s_addc_u32 s3, s23, 0
	s_add_i32 s37, s35, 0x4000
	global_load_lds_dwordx4 v134, s[22:23]
	s_mov_b32 m0, s37
	s_add_i32 s40, s35, 0x6000
	global_load_lds_dwordx4 v130, s[2:3]
	s_mov_b32 m0, s40
	v_mov_b32_e32 v135, v133
	global_load_lds_dwordx4 v134, s[2:3]
	s_cmp_eq_u32 s6, 1
	s_mov_b32 s46, 32
	s_mov_b32 s43, 0
	v_mov_b32_e32 v137, v133
	v_lshl_add_u64 v[2:3], s[22:23], 0, v[130:131]
	s_cselect_b64 s[2:3], -1, 0
	s_setprio 1
	s_cmp_lg_u32 s6, 1
	v_lshl_add_u64 v[4:5], s[22:23], 0, v[134:135]
	v_writelane_b32 v252, s9, 25
	s_cbranch_scc1 .LBB0_1034
	s_setprio 0
	s_barrier

; template <class Epi, class Sched, bool ABLK = false, bool ALIGN_EPI = true, bool SP2 = true, bool BBLK = true>
; __device__ __forceinline__ void gemm_phase(LAS unsigned char* lds, const Gemm g, const Sched& S, const Epi& E) {
;     const int tid = tid_fresh(), wid = __builtin_amdgcn_readfirstlane(tid >> 6), lane = tid & 63, wr = wid >> 2, wc = wid & 3, fr = lane & 15, fq = lane >> 4;
;     unsigned voffA[2], voffB[2];
; #pragma unroll
;     for (int i = 0; i < 2; ++i) { int R, C; stage_rc(tid * 16 + i * 8192, R, C); const int r32 = Epi::PERM ? perm32(R & 31) : (R & 31);
;         const int Rb = Epi::ADJ ? 64 * (R >> 5) + r32 : (R & ~31) + r32;
;         voffA[i] = (unsigned)(R * (ABLK ? 64 : g.lda) + C) * 2u; voffB[i] = BBLK ? (unsigned)(R * 64 + C) * 2u : (unsigned)(Rb * g.ldb + C) * 2u; }
;     const size_t kstep = (size_t)(BK * 2);
;     const size_t hstepA = (size_t)HALF * (ABLK ? 64 : g.lda) * 2, hstepB = BBLK ? (size_t)16384 : (size_t)(Epi::ADJ ? 32 : HALF) * g.ldb * 2;
;     const size_t tstepB = BBLK ? ((size_t)g.ldb / 64) * 32768 : (size_t)BM * g.ldb * 2;
;     const size_t kstepB = BBLK ? (size_t)32768 : kstep;
;     auto b_k0 = [&](int k0) -> size_t { return BBLK ? (size_t)(k0 / BK) * 32768 : (size_t)k0 * 2; };
;     const unsigned ldsw = (unsigned)wid * 1024u;
;     const int aoff = lds_byte(wr * 64 + fr, fq * 8), boff = lds_byte(wc * 32 + fr, fq * 8);
;     ...
;     Unit cur, nxt; int ui = 0;
;     if (!S.next(0, cur)) return;
;     f32x4 acc[2][2][4][2];
; #pragma unroll
;     for (int a = 0; a < 2; ++a)
; #pragma unroll
;         for (int b = 0; b < 2; ++b)
; #pragma unroll
;             for (int m = 0; m < 4; ++m)
; #pragma unroll
;                 for (int n = 0; n < 2; ++n) acc[a][b][m][n] = (f32x4){0.f, 0.f, 0.f, 0.f};
;     bf16x8 At[4][2], B0[2][2], B1[2][2];
;     auto a_unit = [&](const Unit& u) -> const char* { return ABLK ? (const char*)g.A + (size_t)u.pm * ((size_t)g.lda / 64) * 32768 : (const char*)g.A + (size_t)u.pm * 2 * hstepA; };
;     auto a_tile = [&](const char* ub, int tau) -> const char* { return ub + (size_t)tau * (ABLK ? (size_t)32768 : kstep); };
;     const char* uA = a_unit(cur); int tbA = cur.k0 / BK;
;     const char* cA = a_tile(uA, tbA); const char* cB = (const char*)g.Bt + (size_t)cur.pn * tstepB + b_k0(cur.k0);
;     S.a_ready(cur);
;     if constexpr (SP2) {
.LBB0_1155:
	s_or_b64 exec, exec, s[2:3]
	v_readlane_b32 s4, v252, 14
	v_readlane_b32 s5, v252, 15
	v_mov_b32_e32 v9, v0
	s_waitcnt lgkmcnt(0)
	v_cndmask_b32_e64 v2, 0, 1, s[4:5]
	v_cmp_ne_u32_e64 s[2:3], 1, v2
	s_barrier
	s_nop 0
	v_writelane_b32 v252, s2, 26
	s_andn2_b64 vcc, exec, s[4:5]
	v_readfirstlane_b32 s6, v9
	v_writelane_b32 v252, s3, 27
	s_cbranch_vccnz .LBB0_1171
	v_lshlrev_b32_e32 v2, 4, v9
	v_add_u32_e32 v3, 0x2000, v2
	v_ashrrev_i32_e32 v4, 31, v3
	v_lshrrev_b32_e32 v4, 22, v4
	v_add_u32_e32 v4, v3, v4
	v_ashrrev_i32_e32 v6, 10, v4
	v_mul_i32_i24_e32 v5, 0x400, v6
	v_sub_u32_e32 v3, v3, v5
	v_lshrrev_b32_e32 v5, 4, v3
	v_bitop3_b32 v3, v5, v3, 32 bitop3:0x6c
	v_ashrrev_i32_e32 v5, 31, v3
	v_lshrrev_b32_e32 v5, 26, v5
	v_add_u32_e32 v5, v3, v5
	v_ashrrev_i32_e32 v7, 6, v5
	v_and_b32_e32 v5, 0xc0, v5
	v_sub_u32_e32 v3, v3, v5
	v_mov_b32_e32 v5, 1
	v_lshlrev_b32_e32 v4, 5, v6
	v_ashrrev_i16_sdwa v3, v5, sext(v3) dst_sel:DWORD dst_unused:UNUSED_PAD src0_sel:DWORD src1_sel:BYTE_0
	v_and_b32_e32 v4, 32, v4
	v_bfe_i32 v8, v3, 0, 16
	v_add_u32_e32 v3, v4, v8
	v_lshlrev_b32_e32 v4, 3, v6
	v_and_b32_e32 v4, -16, v4
	v_add_u32_e32 v4, v7, v4
	v_lshlrev_b32_e32 v10, 7, v4
	v_lshl_add_u32 v130, v3, 1, v10
	s_movk_i32 s4, 0xf80
	v_mad_u64_u32 v[132:133], s[2:3], v4, s4, v[130:131]
	v_bfe_i32 v4, v9, 27, 1
	v_lshrrev_b32_e32 v4, 22, v4
	v_add_u32_e32 v4, v2, v4
	v_and_b32_e32 v4, 0xfffffc00, v4
	v_sub_u32_e32 v2, v2, v4
	v_lshrrev_b32_e32 v4, 4, v2
	v_bitop3_b32 v4, v4, v2, 32 bitop3:0x6c
	v_ashrrev_i32_e32 v2, 31, v2
	v_lshrrev_b32_e32 v2, 26, v2
	v_ashrrev_i32_e32 v3, 31, v9
	v_add_u32_e32 v2, v4, v2
	v_lshrrev_b32_e32 v3, 26, v3
	v_ashrrev_i32_e32 v11, 6, v2
	v_add_u32_e32 v3, v9, v3
	v_mul_i32_i24_e32 v2, 64, v11
	v_ashrrev_i32_e32 v10, 6, v3
	v_sub_u32_e32 v2, v4, v2
	v_lshlrev_b32_e32 v3, 5, v10
	v_ashrrev_i16_sdwa v2, v5, sext(v2) dst_sel:DWORD dst_unused:UNUSED_PAD src0_sel:DWORD src1_sel:BYTE_0
	v_and_b32_e32 v3, 32, v3
	v_bfe_i32 v12, v2, 0, 16
	v_add_u32_e32 v2, v3, v12
	v_lshlrev_b32_e32 v3, 3, v10
	v_and_b32_e32 v3, -16, v3
	v_add_u32_e32 v3, v11, v3
	v_readlane_b32 s8, v252, 19
	v_lshlrev_b32_e32 v4, 7, v3
	v_readlane_b32 s10, v252, 21
	v_lshl_add_u32 v134, v2, 1, v4
	v_readlane_b32 s11, v252, 22
	s_add_u32 s40, s10, 0x8900000
	v_mad_u64_u32 v[136:137], s[2:3], v3, s4, v[134:135]
	s_addc_u32 s41, s11, 0
	s_lshr_b32 s2, s70, 30
	s_add_i32 s2, s70, s2
	s_ashr_i32 s22, s2, 2
	s_sub_i32 s2, s91, s22
	s_lshl_b32 s2, s2, 2
	s_add_i32 s24, s2, s70
	s_ashr_i32 s8, s6, 6
	s_ashr_i32 s23, s22, 31
	s_ashr_i32 s25, s24, 31
	s_ashr_i32 s7, s6, 8
	s_lshl_b32 s42, s8, 10
	s_lshl_b64 s[2:3], s[22:23], 20
	s_lshl_b64 s[4:5], s[24:25], 20
	s_add_u32 s28, s40, s4
	s_addc_u32 s29, s41, s5
	s_add_i32 s25, s42, 0
	s_add_i32 m0, s25, 0x10000
	v_mov_b32_e32 v139, 0
	global_load_lds_dwordx4 v134, s[28:29]
	s_add_i32 m0, s25, 0x12000
	s_add_u32 s4, s28, 0x4000
	global_load_lds_dwordx4 v130, s[28:29]
	s_addc_u32 s5, s29, 0
	s_add_i32 m0, s25, 0x14000
	v_mov_b32_e32 v137, v139
	global_load_lds_dwordx4 v134, s[4:5]
	s_add_i32 m0, s25, 0x16000
	s_add_u32 s26, s59, s2
	s_addc_u32 s27, s62, s3
	s_add_i32 s43, s25, 0x2000
	global_load_lds_dwordx4 v130, s[4:5]
	s_mov_b32 m0, s25
	s_add_u32 s2, s26, 0x80000
	global_load_lds_dwordx4 v136, s[26:27]
	s_mov_b32 m0, s43
	s_addc_u32 s3, s27, 0
	s_add_i32 s44, s25, 0x4000
	global_load_lds_dwordx4 v132, s[26:27]
	s_mov_b32 m0, s44
	s_add_i32 s45, s25, 0x6000
	global_load_lds_dwordx4 v136, s[2:3]
	s_mov_b32 m0, s45
	v_mov_b32_e32 v133, v139
	global_load_lds_dwordx4 v132, s[2:3]
	s_cmp_eq_u32 s7, 1
	s_mov_b32 s46, 0
	v_mov_b32_e32 v135, v139
	v_mov_b32_e32 v131, v139
	s_mov_b64 s[4:5], 0x4000
	v_lshl_add_u64 v[2:3], s[26:27], 0, v[136:137]
	s_cselect_b64 s[2:3], -1, 0
	s_setprio 1
	s_cmp_lg_u32 s7, 1
	v_lshl_add_u64 v[4:5], s[26:27], 0, v[132:133]
	v_readlane_b32 s9, v252, 20
	s_cbranch_scc1 .LBB0_1158
	s_setprio 0
	s_barrier

; template <class Epi, class Sched, bool ABLK = false, bool ALIGN_EPI = true, bool SP2 = true, bool BBLK = true>
; __device__ __forceinline__ void gemm_phase(LAS unsigned char* lds, const Gemm g, const Sched& S, const Epi& E) {
;     const int tid = tid_fresh(), wid = __builtin_amdgcn_readfirstlane(tid >> 6), lane = tid & 63, wr = wid >> 2, wc = wid & 3, fr = lane & 15, fq = lane >> 4;
;     unsigned voffA[2], voffB[2];
; #pragma unroll
;     for (int i = 0; i < 2; ++i) { int R, C; stage_rc(tid * 16 + i * 8192, R, C); const int r32 = Epi::PERM ? perm32(R & 31) : (R & 31);
;         const int Rb = Epi::ADJ ? 64 * (R >> 5) + r32 : (R & ~31) + r32;
;         voffA[i] = (unsigned)(R * (ABLK ? 64 : g.lda) + C) * 2u; voffB[i] = BBLK ? (unsigned)(R * 64 + C) * 2u : (unsigned)(Rb * g.ldb + C) * 2u; }
;     const size_t kstep = (size_t)(BK * 2);
;     const size_t hstepA = (size_t)HALF * (ABLK ? 64 : g.lda) * 2, hstepB = BBLK ? (size_t)16384 : (size_t)(Epi::ADJ ? 32 : HALF) * g.ldb * 2;
;     const size_t tstepB = BBLK ? ((size_t)g.ldb / 64) * 32768 : (size_t)BM * g.ldb * 2;
;     const size_t kstepB = BBLK ? (size_t)32768 : kstep;
;     auto b_k0 = [&](int k0) -> size_t { return BBLK ? (size_t)(k0 / BK) * 32768 : (size_t)k0 * 2; };
;     const unsigned ldsw = (unsigned)wid * 1024u;
;     const int aoff = lds_byte(wr * 64 + fr, fq * 8), boff = lds_byte(wc * 32 + fr, fq * 8);
;     ...
;     Unit cur, nxt; int ui = 0;
;     if (!S.next(0, cur)) return;
;     f32x4 acc[2][2][4][2];
; #pragma unroll
;     for (int a = 0; a < 2; ++a)
; #pragma unroll
;         for (int b = 0; b < 2; ++b)
; #pragma unroll
;             for (int m = 0; m < 4; ++m)
; #pragma unroll
;                 for (int n = 0; n < 2; ++n) acc[a][b][m][n] = (f32x4){0.f, 0.f, 0.f, 0.f};
;     bf16x8 At[4][2], B0[2][2], B1[2][2];
;     auto a_unit = [&](const Unit& u) -> const char* { return ABLK ? (const char*)g.A + (size_t)u.pm * ((size_t)g.lda / 64) * 32768 : (const char*)g.A + (size_t)u.pm * 2 * hstepA; };
;     auto a_tile = [&](const char* ub, int tau) -> const char* { return ub + (size_t)tau * (ABLK ? (size_t)32768 : kstep); };
;     const char* uA = a_unit(cur); int tbA = cur.k0 / BK;
;     const char* cA = a_tile(uA, tbA); const char* cB = (const char*)g.Bt + (size_t)cur.pn * tstepB + b_k0(cur.k0);
;     S.a_ready(cur);
;     if constexpr (SP2) {
.LBB0_1223:
	s_or_b64 exec, exec, s[2:3]
	v_mov_b32_e32 v4, v0
	s_waitcnt lgkmcnt(0)
	s_barrier
	v_readlane_b32 s4, v252, 19
	v_bfe_i32 v3, v4, 27, 1
	v_lshlrev_b32_e32 v6, 4, v4
	v_lshrrev_b32_e32 v3, 22, v3
	v_add_u32_e32 v3, v6, v3
	v_and_b32_e32 v3, 0xfffffc00, v3
	v_sub_u32_e32 v3, v6, v3
	v_lshrrev_b32_e32 v5, 4, v3
	v_bitop3_b32 v5, v5, v3, 32 bitop3:0x6c
	v_ashrrev_i32_e32 v3, 31, v3
	v_lshrrev_b32_e32 v3, 26, v3
	v_ashrrev_i32_e32 v2, 31, v4
	v_add_u32_e32 v3, v5, v3
	v_lshrrev_b32_e32 v2, 26, v2
	v_ashrrev_i32_e32 v3, 6, v3
	v_add_u32_e32 v2, v4, v2
	v_mul_i32_i24_e32 v9, 64, v3
	v_ashrrev_i32_e32 v2, 6, v2
	v_sub_u32_e32 v5, v5, v9
	v_mov_b32_e32 v9, 1
	v_lshlrev_b32_e32 v7, 3, v2
	v_lshlrev_b32_e32 v8, 5, v2
	v_ashrrev_i16_sdwa v5, v9, sext(v5) dst_sel:DWORD dst_unused:UNUSED_PAD src0_sel:DWORD src1_sel:BYTE_0
	v_and_b32_e32 v7, 0x1fffff0, v7
	v_and_b32_e32 v8, 32, v8
	v_bfe_i32 v5, v5, 0, 16
	v_add_u32_e32 v8, v8, v5
	v_add_lshl_u32 v7, v3, v7, 7
	v_lshl_add_u32 v130, v8, 1, v7
	v_add_u32_e32 v7, 0x2000, v6
	v_ashrrev_i32_e32 v6, 31, v7
	v_lshrrev_b32_e32 v6, 22, v6
	v_add_u32_e32 v6, v7, v6
	v_ashrrev_i32_e32 v6, 10, v6
	v_mul_i32_i24_e32 v8, 0x400, v6
	v_sub_u32_e32 v7, v7, v8
	v_lshrrev_b32_e32 v8, 4, v7
	v_bitop3_b32 v8, v8, v7, 32 bitop3:0x6c
	v_lshlrev_b32_e32 v7, 3, v6
	v_readlane_b32 s6, v252, 21
	v_and_b32_e32 v10, 0x1fffff0, v7
	v_ashrrev_i32_e32 v7, 31, v8
	v_readlane_b32 s5, v252, 20
	v_readlane_b32 s7, v252, 22
	s_add_u32 s30, s6, 0x10900000
	v_readfirstlane_b32 s4, v4
	v_lshrrev_b32_e32 v7, 26, v7
	s_addc_u32 s31, s7, 0
	s_ashr_i32 s5, s4, 6
	v_add_u32_e32 v11, v8, v7
	v_ashrrev_i32_e32 v7, 6, v11
	v_and_b32_e32 v11, 0xc0, v11
	s_ashr_i32 s6, s4, 8
	s_lshl_b32 s34, s5, 10
	v_readlane_b32 s2, v252, 16
	v_sub_u32_e32 v8, v8, v11
	s_add_u32 s22, s30, s2
	v_lshlrev_b32_e32 v12, 5, v6
	v_ashrrev_i16_sdwa v8, v9, sext(v8) dst_sel:DWORD dst_unused:UNUSED_PAD src0_sel:DWORD src1_sel:BYTE_0
	s_addc_u32 s23, s31, 0
	s_add_i32 s35, s34, 0
	v_and_b32_e32 v12, 32, v12
	v_bfe_i32 v8, v8, 0, 16
	s_add_i32 m0, s35, 0x10000
	v_add_u32_e32 v9, v12, v8
	v_add_lshl_u32 v10, v7, v10, 7
	global_load_lds_dwordx4 v130, s[22:23]
	s_add_i32 m0, s35, 0x12000
	v_lshl_add_u32 v132, v9, 1, v10
	s_add_u32 s2, s22, 0x4000
	global_load_lds_dwordx4 v132, s[22:23]
	s_addc_u32 s3, s23, 0
	s_add_i32 m0, s35, 0x14000
	v_mov_b32_e32 v131, 0
	global_load_lds_dwordx4 v130, s[2:3]
	s_add_i32 m0, s35, 0x16000
	s_mov_b32 s43, 0
	global_load_lds_dwordx4 v132, s[2:3]
	v_readlane_b32 s2, v252, 17
	v_readlane_b32 s3, v252, 18
	s_add_u32 s24, s1, s2
	s_addc_u32 s25, s33, s3
	s_add_i32 s36, s35, 0x2000
	s_mov_b32 m0, s35
	s_add_u32 s2, s24, 0x4000
	global_load_lds_dwordx4 v130, s[24:25]
	s_mov_b32 m0, s36
	s_addc_u32 s3, s25, 0
	s_add_i32 s37, s35, 0x4000
	global_load_lds_dwordx4 v132, s[24:25]
	s_mov_b32 m0, s37
	s_add_i32 s40, s35, 0x6000
	global_load_lds_dwordx4 v130, s[2:3]
	s_mov_b32 m0, s40
	s_cmp_eq_u32 s6, 1
	global_load_lds_dwordx4 v132, s[2:3]
	s_cselect_b64 s[2:3], -1, 0
	s_setprio 1
	s_cmp_lg_u32 s6, 1
	v_mov_b32_e32 v133, v131
	s_cbranch_scc1 .LBB0_1225
	s_setprio 0
	s_barrier

; template <class Epi, class Sched, bool ABLK = false, bool ALIGN_EPI = true, bool SP2 = true, bool BBLK = true>
; __device__ __forceinline__ void gemm_phase(LAS unsigned char* lds, const Gemm g, const Sched& S, const Epi& E) {
;     const int tid = tid_fresh(), wid = __builtin_amdgcn_readfirstlane(tid >> 6), lane = tid & 63, wr = wid >> 2, wc = wid & 3, fr = lane & 15, fq = lane >> 4;
;     unsigned voffA[2], voffB[2];
; #pragma unroll
;     for (int i = 0; i < 2; ++i) { int R, C; stage_rc(tid * 16 + i * 8192, R, C); const int r32 = Epi::PERM ? perm32(R & 31) : (R & 31);
;         const int Rb = Epi::ADJ ? 64 * (R >> 5) + r32 : (R & ~31) + r32;
;         voffA[i] = (unsigned)(R * (ABLK ? 64 : g.lda) + C) * 2u; voffB[i] = BBLK ? (unsigned)(R * 64 + C) * 2u : (unsigned)(Rb * g.ldb + C) * 2u; }
;     const size_t kstep = (size_t)(BK * 2);
;     const size_t hstepA = (size_t)HALF * (ABLK ? 64 : g.lda) * 2, hstepB = BBLK ? (size_t)16384 : (size_t)(Epi::ADJ ? 32 : HALF) * g.ldb * 2;
;     const size_t tstepB = BBLK ? ((size_t)g.ldb / 64) * 32768 : (size_t)BM * g.ldb * 2;
;     const size_t kstepB = BBLK ? (size_t)32768 : kstep;
;     auto b_k0 = [&](int k0) -> size_t { return BBLK ? (size_t)(k0 / BK) * 32768 : (size_t)k0 * 2; };
;     const unsigned ldsw = (unsigned)wid * 1024u;
;     const int aoff = lds_byte(wr * 64 + fr, fq * 8), boff = lds_byte(wc * 32 + fr, fq * 8);
;     ...
;     Unit cur, nxt; int ui = 0;
;     if (!S.next(0, cur)) return;
;     f32x4 acc[2][2][4][2];
; #pragma unroll
;     for (int a = 0; a < 2; ++a)
; #pragma unroll
;         for (int b = 0; b < 2; ++b)
; #pragma unroll
;             for (int m = 0; m < 4; ++m)
; #pragma unroll
;                 for (int n = 0; n < 2; ++n) acc[a][b][m][n] = (f32x4){0.f, 0.f, 0.f, 0.f};
;     bf16x8 At[4][2], B0[2][2], B1[2][2];
;     auto a_unit = [&](const Unit& u) -> const char* { return ABLK ? (const char*)g.A + (size_t)u.pm * ((size_t)g.lda / 64) * 32768 : (const char*)g.A + (size_t)u.pm * 2 * hstepA; };
;     auto a_tile = [&](const char* ub, int tau) -> const char* { return ub + (size_t)tau * (ABLK ? (size_t)32768 : kstep); };
;     const char* uA = a_unit(cur); int tbA = cur.k0 / BK;
;     const char* cA = a_tile(uA, tbA); const char* cB = (const char*)g.Bt + (size_t)cur.pn * tstepB + b_k0(cur.k0);
;     S.a_ready(cur);
;     if constexpr (SP2) {
.LBB0_1346:
	s_or_b64 exec, exec, s[2:3]
	s_add_u32 s76, s68, 0x1b900000
	s_addc_u32 s33, s69, 0
	s_add_u32 s90, s68, 0x1e100000
	s_addc_u32 s91, s69, 0
	v_readlane_b32 s2, v252, 26
	s_add_u32 s62, s68, 0x23100000
	v_mov_b32_e32 v9, v0
	v_readlane_b32 s3, v252, 27
	s_waitcnt lgkmcnt(0)
	s_barrier
	s_addc_u32 s83, s69, 0
	s_and_b64 vcc, exec, s[2:3]
	v_readfirstlane_b32 s4, v9
	s_cbranch_vccnz .LBB0_1366
	v_lshlrev_b32_e32 v2, 4, v9
	v_add_u32_e32 v3, 0x2000, v2
	v_ashrrev_i32_e32 v4, 31, v3
	v_lshrrev_b32_e32 v4, 22, v4
	v_add_u32_e32 v4, v3, v4
	v_ashrrev_i32_e32 v6, 10, v4
	v_mul_i32_i24_e32 v5, 0x400, v6
	v_sub_u32_e32 v3, v3, v5
	v_lshrrev_b32_e32 v5, 4, v3
	v_bitop3_b32 v3, v5, v3, 32 bitop3:0x6c
	v_ashrrev_i32_e32 v5, 31, v3
	v_lshrrev_b32_e32 v5, 26, v5
	v_add_u32_e32 v5, v3, v5
	v_ashrrev_i32_e32 v7, 6, v5
	v_and_b32_e32 v5, 0xc0, v5
	v_sub_u32_e32 v3, v3, v5
	v_mov_b32_e32 v5, 1
	v_lshlrev_b32_e32 v4, 5, v6
	v_ashrrev_i16_sdwa v3, v5, sext(v3) dst_sel:DWORD dst_unused:UNUSED_PAD src0_sel:DWORD src1_sel:BYTE_0
	v_and_b32_e32 v4, 32, v4
	v_bfe_i32 v8, v3, 0, 16
	v_add_u32_e32 v3, v4, v8
	v_lshlrev_b32_e32 v4, 3, v6
	v_and_b32_e32 v4, -16, v4
	v_add_u32_e32 v4, v7, v4
	v_lshlrev_b32_e32 v10, 7, v4
	v_lshl_add_u32 v130, v3, 1, v10
	s_movk_i32 s6, 0xf80
	v_mad_u64_u32 v[132:133], s[2:3], v4, s6, v[130:131]
	v_bfe_i32 v4, v9, 27, 1
	v_lshrrev_b32_e32 v4, 22, v4
	v_add_u32_e32 v4, v2, v4
	v_and_b32_e32 v4, 0xfffffc00, v4
	v_sub_u32_e32 v2, v2, v4
	v_lshrrev_b32_e32 v4, 4, v2
	v_bitop3_b32 v4, v4, v2, 32 bitop3:0x6c
	v_ashrrev_i32_e32 v2, 31, v2
	v_lshrrev_b32_e32 v2, 26, v2
	v_ashrrev_i32_e32 v3, 31, v9
	v_add_u32_e32 v2, v4, v2
	v_lshrrev_b32_e32 v3, 26, v3
	v_ashrrev_i32_e32 v11, 6, v2
	v_add_u32_e32 v3, v9, v3
	v_mul_i32_i24_e32 v2, 64, v11
	v_ashrrev_i32_e32 v10, 6, v3
	v_sub_u32_e32 v2, v4, v2
	v_lshlrev_b32_e32 v3, 5, v10
	v_ashrrev_i16_sdwa v2, v5, sext(v2) dst_sel:DWORD dst_unused:UNUSED_PAD src0_sel:DWORD src1_sel:BYTE_0
	v_and_b32_e32 v3, 32, v3
	v_bfe_i32 v12, v2, 0, 16
	v_add_u32_e32 v2, v3, v12
	v_lshlrev_b32_e32 v3, 3, v10
	v_and_b32_e32 v3, -16, v3
	v_add_u32_e32 v3, v11, v3
	v_lshlrev_b32_e32 v4, 7, v3
	v_lshl_add_u32 v134, v2, 1, v4
	s_add_u32 s1, s68, 0x4100000
	v_mad_u64_u32 v[136:137], s[2:3], v3, s6, v[134:135]
	s_addc_u32 s48, s69, 0
	s_lshr_b32 s2, s70, 30
	s_add_i32 s2, s70, s2
	s_ashr_i32 s34, s2, 2
	v_readlane_b32 s2, v252, 23
	s_sub_i32 s2, s2, s34
	s_lshl_b32 s2, s2, 2
	s_add_i32 s30, s2, s70
	s_ashr_i32 s8, s4, 6
	s_ashr_i32 s35, s34, 31
	s_ashr_i32 s31, s30, 31
	s_ashr_i32 s5, s4, 8
	s_lshl_b32 s49, s8, 10
	s_lshl_b64 s[2:3], s[34:35], 20
	s_lshl_b64 s[6:7], s[30:31], 20
	s_add_u32 s40, s1, s6
	s_addc_u32 s41, s48, s7
	s_add_i32 s31, s49, 0
	s_add_i32 m0, s31, 0x10000
	v_mov_b32_e32 v139, 0
	global_load_lds_dwordx4 v134, s[40:41]
	s_add_i32 m0, s31, 0x12000
	s_add_u32 s6, s40, 0x4000
	global_load_lds_dwordx4 v130, s[40:41]
	s_addc_u32 s7, s41, 0
	s_add_i32 m0, s31, 0x14000
	v_mov_b32_e32 v137, v139
	global_load_lds_dwordx4 v134, s[6:7]
	s_add_i32 m0, s31, 0x16000
	s_add_u32 s36, s76, s2
	s_addc_u32 s37, s33, s3
	s_add_i32 s35, s31, 0x2000
	global_load_lds_dwordx4 v130, s[6:7]
	s_mov_b32 m0, s31
	s_add_u32 s2, s36, 0x80000
	global_load_lds_dwordx4 v136, s[36:37]
	s_mov_b32 m0, s35
	s_addc_u32 s3, s37, 0
	s_add_i32 s50, s31, 0x4000
	global_load_lds_dwordx4 v132, s[36:37]
	s_mov_b32 m0, s50
	s_add_i32 s51, s31, 0x6000
	global_load_lds_dwordx4 v136, s[2:3]
	s_mov_b32 m0, s51
	v_mov_b32_e32 v133, v139
	global_load_lds_dwordx4 v132, s[2:3]
	s_cmp_eq_u32 s5, 1
	s_mov_b32 s52, 0
	v_mov_b32_e32 v135, v139
	v_mov_b32_e32 v131, v139
	v_lshl_add_u64 v[4:5], s[36:37], 0, v[136:137]
	v_lshl_add_u64 v[2:3], s[36:37], 0, v[132:133]
	s_cselect_b64 s[2:3], -1, 0
	s_setprio 1
	s_cmp_lg_u32 s5, 1
	s_mov_b64 s[6:7], 0x80000
	s_cbranch_scc1 .LBB0_1349
	s_setprio 0
	s_barrier

; template <class Epi, class Sched, bool ABLK = false, bool ALIGN_EPI = true, bool SP2 = true, bool BBLK = true>
; __device__ __forceinline__ void gemm_phase(LAS unsigned char* lds, const Gemm g, const Sched& S, const Epi& E) {
;     const int tid = tid_fresh(), wid = __builtin_amdgcn_readfirstlane(tid >> 6), lane = tid & 63, wr = wid >> 2, wc = wid & 3, fr = lane & 15, fq = lane >> 4;
;     unsigned voffA[2], voffB[2];
; #pragma unroll
;     for (int i = 0; i < 2; ++i) { int R, C; stage_rc(tid * 16 + i * 8192, R, C); const int r32 = Epi::PERM ? perm32(R & 31) : (R & 31);
;         const int Rb = Epi::ADJ ? 64 * (R >> 5) + r32 : (R & ~31) + r32;
;         voffA[i] = (unsigned)(R * (ABLK ? 64 : g.lda) + C) * 2u; voffB[i] = BBLK ? (unsigned)(R * 64 + C) * 2u : (unsigned)(Rb * g.ldb + C) * 2u; }
;     const size_t kstep = (size_t)(BK * 2);
;     const size_t hstepA = (size_t)HALF * (ABLK ? 64 : g.lda) * 2, hstepB = BBLK ? (size_t)16384 : (size_t)(Epi::ADJ ? 32 : HALF) * g.ldb * 2;
;     const size_t tstepB = BBLK ? ((size_t)g.ldb / 64) * 32768 : (size_t)BM * g.ldb * 2;
;     const size_t kstepB = BBLK ? (size_t)32768 : kstep;
;     auto b_k0 = [&](int k0) -> size_t { return BBLK ? (size_t)(k0 / BK) * 32768 : (size_t)k0 * 2; };
;     const unsigned ldsw = (unsigned)wid * 1024u;
;     const int aoff = lds_byte(wr * 64 + fr, fq * 8), boff = lds_byte(wc * 32 + fr, fq * 8);
;     ...
;     Unit cur, nxt; int ui = 0;
;     if (!S.next(0, cur)) return;
;     f32x4 acc[2][2][4][2];
; #pragma unroll
;     for (int a = 0; a < 2; ++a)
; #pragma unroll
;         for (int b = 0; b < 2; ++b)
; #pragma unroll
;             for (int m = 0; m < 4; ++m)
; #pragma unroll
;                 for (int n = 0; n < 2; ++n) acc[a][b][m][n] = (f32x4){0.f, 0.f, 0.f, 0.f};
;     bf16x8 At[4][2], B0[2][2], B1[2][2];
;     auto a_unit = [&](const Unit& u) -> const char* { return ABLK ? (const char*)g.A + (size_t)u.pm * ((size_t)g.lda / 64) * 32768 : (const char*)g.A + (size_t)u.pm * 2 * hstepA; };
;     auto a_tile = [&](const char* ub, int tau) -> const char* { return ub + (size_t)tau * (ABLK ? (size_t)32768 : kstep); };
;     const char* uA = a_unit(cur); int tbA = cur.k0 / BK;
;     const char* cA = a_tile(uA, tbA); const char* cB = (const char*)g.Bt + (size_t)cur.pn * tstepB + b_k0(cur.k0);
;     S.a_ready(cur);
;     if constexpr (SP2) {
.LBB0_1710:
	s_or_b64 exec, exec, s[2:3]
	s_waitcnt vmcnt(2)
	v_mov_b32_e32 v7, v0
	s_waitcnt lgkmcnt(0)
	s_barrier
	s_movk_i32 s6, 0xf080
	v_ashrrev_i32_e32 v2, 31, v7
	v_lshrrev_b32_e32 v2, 26, v2
	v_add_u32_e32 v2, v7, v2
	v_ashrrev_i32_e32 v6, 6, v2
	v_bfe_i32 v2, v7, 27, 1
	v_lshlrev_b32_e32 v1, 4, v7
	v_lshrrev_b32_e32 v2, 22, v2
	v_add_u32_e32 v2, v1, v2
	v_and_b32_e32 v2, 0xfffffc00, v2
	v_sub_u32_e32 v2, v1, v2
	v_lshrrev_b32_e32 v3, 4, v2
	v_bitop3_b32 v3, v3, v2, 32 bitop3:0x6c
	v_ashrrev_i32_e32 v2, 31, v2
	v_lshrrev_b32_e32 v2, 26, v2
	v_add_u32_e32 v2, v3, v2
	v_ashrrev_i32_e32 v8, 6, v2
	v_lshlrev_b32_e32 v4, 3, v6
	v_mul_i32_i24_e32 v5, 64, v8
	v_and_b32_e32 v4, -16, v4
	v_sub_u32_e32 v3, v3, v5
	v_mov_b32_e32 v5, 1
	v_add_u32_e32 v2, v8, v4
	v_lshlrev_b32_e32 v4, 5, v6
	v_ashrrev_i16_sdwa v3, v5, sext(v3) dst_sel:DWORD dst_unused:UNUSED_PAD src0_sel:DWORD src1_sel:BYTE_0
	v_and_b32_e32 v4, 32, v4
	v_bfe_i32 v9, v3, 0, 16
	v_add_u32_e32 v3, v4, v9
	v_lshlrev_b32_e32 v4, 12, v2
	v_lshl_add_u32 v130, v3, 1, v4
	v_add_u32_e32 v1, 0x2000, v1
	v_mad_u64_u32 v[132:133], s[2:3], v2, s6, v[130:131]
	v_ashrrev_i32_e32 v2, 31, v1
	v_lshrrev_b32_e32 v2, 22, v2
	v_add_u32_e32 v2, v1, v2
	s_waitcnt vmcnt(1)
	v_ashrrev_i32_e32 v10, 10, v2
	v_mul_i32_i24_e32 v2, 0x400, v10
	v_sub_u32_e32 v1, v1, v2
	v_lshrrev_b32_e32 v2, 4, v1
	v_bitop3_b32 v1, v2, v1, 32 bitop3:0x6c
	v_ashrrev_i32_e32 v3, 31, v1
	v_lshrrev_b32_e32 v3, 26, v3
	v_add_u32_e32 v3, v1, v3
	v_ashrrev_i32_e32 v11, 6, v3
	v_and_b32_e32 v3, 0xc0, v3
	v_lshlrev_b32_e32 v2, 3, v10
	v_sub_u32_e32 v1, v1, v3
	s_add_u32 s1, s68, 0x2d100000
	v_and_b32_e32 v2, -16, v2
	v_lshlrev_b32_e32 v4, 5, v10
	v_ashrrev_i16_sdwa v1, v5, sext(v1) dst_sel:DWORD dst_unused:UNUSED_PAD src0_sel:DWORD src1_sel:BYTE_0
	s_addc_u32 s36, s69, 0
	v_add_u32_e32 v2, v11, v2
	v_and_b32_e32 v4, 32, v4
	v_bfe_i32 v12, v1, 0, 16
	s_add_u32 s37, s68, 0x6100000
	v_readfirstlane_b32 s4, v7
	v_add_u32_e32 v1, v4, v12
	v_lshlrev_b32_e32 v3, 12, v2
	s_addc_u32 s38, s69, 0
	s_ashr_i32 s5, s4, 6
	v_lshl_add_u32 v134, v1, 1, v3
	v_mad_u64_u32 v[136:137], s[2:3], v2, s6, v[134:135]
	s_ashr_i32 s6, s4, 8
	s_lshl_b32 s39, s5, 10
	s_add_u32 s26, s37, s97
	s_addc_u32 s27, s38, 0
	s_add_i32 s40, s39, 0
	s_add_i32 m0, s40, 0x10000
	v_mov_b32_e32 v133, 0
	global_load_lds_dwordx4 v132, s[26:27]
	s_add_i32 m0, s40, 0x12000
	s_add_u32 s2, s26, 0x4000
	global_load_lds_dwordx4 v136, s[26:27]
	s_addc_u32 s3, s27, 0
	s_add_i32 m0, s40, 0x14000
	v_mov_b32_e32 v131, v133
	global_load_lds_dwordx4 v132, s[2:3]
	s_add_i32 m0, s40, 0x16000
	v_mov_b32_e32 v135, v133
	global_load_lds_dwordx4 v136, s[2:3]
	v_readlane_b32 s2, v252, 24
	v_readlane_b32 s3, v252, 25
	s_add_u32 s28, s1, s2
	s_addc_u32 s29, s36, s3
	s_add_i32 s41, s40, 0x2000
	s_mov_b32 m0, s40
	s_add_u32 s2, s28, 0x80000
	global_load_lds_dwordx4 v130, s[28:29]
	s_mov_b32 m0, s41
	s_addc_u32 s3, s29, 0
	s_add_i32 s42, s40, 0x4000
	global_load_lds_dwordx4 v134, s[28:29]
	s_mov_b32 m0, s42
	s_add_i32 s43, s40, 0x6000
	global_load_lds_dwordx4 v130, s[2:3]
	s_mov_b32 m0, s43
	s_cmp_eq_u32 s6, 1
	global_load_lds_dwordx4 v134, s[2:3]
	s_mov_b32 s47, 32
	s_mov_b32 s46, 0
	v_mov_b32_e32 v137, v133
	v_lshl_add_u64 v[2:3], s[28:29], 0, v[130:131]
	s_cselect_b64 s[2:3], -1, 0
	s_setprio 1
	s_cmp_lg_u32 s6, 1
	v_lshl_add_u64 v[4:5], s[28:29], 0, v[134:135]
	s_cbranch_scc1 .LBB0_1712
	s_setprio 0
	s_barrier

; template <class Epi, class Sched, bool ABLK = false, bool ALIGN_EPI = true, bool SP2 = true, bool BBLK = true>
; __device__ __forceinline__ void gemm_phase(LAS unsigned char* lds, const Gemm g, const Sched& S, const Epi& E) {
;     const int tid = tid_fresh(), wid = __builtin_amdgcn_readfirstlane(tid >> 6), lane = tid & 63, wr = wid >> 2, wc = wid & 3, fr = lane & 15, fq = lane >> 4;
;     unsigned voffA[2], voffB[2];
; #pragma unroll
;     for (int i = 0; i < 2; ++i) { int R, C; stage_rc(tid * 16 + i * 8192, R, C); const int r32 = Epi::PERM ? perm32(R & 31) : (R & 31);
;         const int Rb = Epi::ADJ ? 64 * (R >> 5) + r32 : (R & ~31) + r32;
;         voffA[i] = (unsigned)(R * (ABLK ? 64 : g.lda) + C) * 2u; voffB[i] = BBLK ? (unsigned)(R * 64 + C) * 2u : (unsigned)(Rb * g.ldb + C) * 2u; }
;     const size_t kstep = (size_t)(BK * 2);
;     const size_t hstepA = (size_t)HALF * (ABLK ? 64 : g.lda) * 2, hstepB = BBLK ? (size_t)16384 : (size_t)(Epi::ADJ ? 32 : HALF) * g.ldb * 2;
;     const size_t tstepB = BBLK ? ((size_t)g.ldb / 64) * 32768 : (size_t)BM * g.ldb * 2;
;     const size_t kstepB = BBLK ? (size_t)32768 : kstep;
;     auto b_k0 = [&](int k0) -> size_t { return BBLK ? (size_t)(k0 / BK) * 32768 : (size_t)k0 * 2; };
;     const unsigned ldsw = (unsigned)wid * 1024u;
;     const int aoff = lds_byte(wr * 64 + fr, fq * 8), boff = lds_byte(wc * 32 + fr, fq * 8);
;     ...
;     Unit cur, nxt; int ui = 0;
;     if (!S.next(0, cur)) return;
;     f32x4 acc[2][2][4][2];
; #pragma unroll
;     for (int a = 0; a < 2; ++a)
; #pragma unroll
;         for (int b = 0; b < 2; ++b)
; #pragma unroll
;             for (int m = 0; m < 4; ++m)
; #pragma unroll
;                 for (int n = 0; n < 2; ++n) acc[a][b][m][n] = (f32x4){0.f, 0.f, 0.f, 0.f};
;     bf16x8 At[4][2], B0[2][2], B1[2][2];
;     auto a_unit = [&](const Unit& u) -> const char* { return ABLK ? (const char*)g.A + (size_t)u.pm * ((size_t)g.lda / 64) * 32768 : (const char*)g.A + (size_t)u.pm * 2 * hstepA; };
;     auto a_tile = [&](const char* ub, int tau) -> const char* { return ub + (size_t)tau * (ABLK ? (size_t)32768 : kstep); };
;     const char* uA = a_unit(cur); int tbA = cur.k0 / BK;
;     const char* cA = a_tile(uA, tbA); const char* cB = (const char*)g.Bt + (size_t)cur.pn * tstepB + b_k0(cur.k0);
;     S.a_ready(cur);
;     if constexpr (SP2) {
.LBB0_1833:
	s_or_b64 exec, exec, s[2:3]
	v_readlane_b32 s2, v252, 26
	s_waitcnt lgkmcnt(0)
	v_mov_b32_e32 v1, v0
	v_readlane_b32 s3, v252, 27
	s_barrier
	s_and_b64 vcc, exec, s[2:3]
	v_readfirstlane_b32 s6, v1
	s_cbranch_vccnz .LBB0_1849
	v_lshlrev_b32_e32 v2, 4, v1
	v_add_u32_e32 v3, 0x2000, v2
	v_ashrrev_i32_e32 v4, 31, v3
	v_lshrrev_b32_e32 v4, 22, v4
	v_add_u32_e32 v4, v3, v4
	v_ashrrev_i32_e32 v6, 10, v4
	v_mul_i32_i24_e32 v5, 0x400, v6
	v_sub_u32_e32 v3, v3, v5
	v_lshrrev_b32_e32 v5, 4, v3
	v_bitop3_b32 v3, v5, v3, 32 bitop3:0x6c
	v_ashrrev_i32_e32 v5, 31, v3
	v_lshrrev_b32_e32 v5, 26, v5
	v_add_u32_e32 v5, v3, v5
	v_ashrrev_i32_e32 v7, 6, v5
	v_and_b32_e32 v5, 0xc0, v5
	v_sub_u32_e32 v3, v3, v5
	v_mov_b32_e32 v5, 1
	v_lshlrev_b32_e32 v4, 5, v6
	v_ashrrev_i16_sdwa v3, v5, sext(v3) dst_sel:DWORD dst_unused:UNUSED_PAD src0_sel:DWORD src1_sel:BYTE_0
	v_and_b32_e32 v4, 32, v4
	v_bfe_i32 v8, v3, 0, 16
	v_add_u32_e32 v3, v4, v8
	v_lshlrev_b32_e32 v4, 3, v6
	v_and_b32_e32 v4, -16, v4
	v_add_u32_e32 v4, v7, v4
	v_lshlrev_b32_e32 v9, 7, v4
	v_lshl_add_u32 v130, v3, 1, v9
	s_movk_i32 s4, 0xf80
	v_mad_u64_u32 v[132:133], s[2:3], v4, s4, v[130:131]
	v_bfe_i32 v4, v1, 27, 1
	v_lshrrev_b32_e32 v4, 22, v4
	v_add_u32_e32 v4, v2, v4
	v_and_b32_e32 v4, 0xfffffc00, v4
	v_sub_u32_e32 v2, v2, v4
	v_lshrrev_b32_e32 v4, 4, v2
	v_bitop3_b32 v4, v4, v2, 32 bitop3:0x6c
	v_ashrrev_i32_e32 v2, 31, v2
	v_lshrrev_b32_e32 v2, 26, v2
	v_ashrrev_i32_e32 v3, 31, v1
	v_add_u32_e32 v2, v4, v2
	v_lshrrev_b32_e32 v3, 26, v3
	v_ashrrev_i32_e32 v10, 6, v2
	v_add_u32_e32 v3, v1, v3
	v_mul_i32_i24_e32 v2, 64, v10
	v_ashrrev_i32_e32 v9, 6, v3
	v_sub_u32_e32 v2, v4, v2
	v_lshlrev_b32_e32 v3, 5, v9
	v_ashrrev_i16_sdwa v2, v5, sext(v2) dst_sel:DWORD dst_unused:UNUSED_PAD src0_sel:DWORD src1_sel:BYTE_0
	v_and_b32_e32 v3, 32, v3
	v_bfe_i32 v11, v2, 0, 16
	v_add_u32_e32 v2, v3, v11
	v_lshlrev_b32_e32 v3, 3, v9
	v_and_b32_e32 v3, -16, v3
	v_add_u32_e32 v3, v10, v3
	v_lshlrev_b32_e32 v4, 7, v3
	v_lshl_add_u32 v134, v2, 1, v4
	s_add_u32 s1, s68, 0xa900000
	v_mad_u64_u32 v[136:137], s[2:3], v3, s4, v[134:135]
	s_addc_u32 s38, s69, 0
	s_lshr_b32 s2, s70, 30
	s_add_i32 s2, s70, s2
	s_ashr_i32 s22, s2, 2
	v_readlane_b32 s2, v252, 23
	s_sub_i32 s2, s2, s22
	s_lshl_b32 s2, s2, 2
	s_add_i32 s24, s2, s70
	s_ashr_i32 s8, s6, 6
	s_ashr_i32 s23, s22, 31
	s_ashr_i32 s25, s24, 31
	s_ashr_i32 s7, s6, 8
	s_lshl_b32 s39, s8, 10
	s_lshl_b64 s[2:3], s[22:23], 20
	s_lshl_b64 s[4:5], s[24:25], 20
	s_add_u32 s28, s1, s4
	s_addc_u32 s29, s38, s5
	s_add_i32 s25, s39, 0
	s_add_i32 m0, s25, 0x10000
	v_mov_b32_e32 v139, 0
	global_load_lds_dwordx4 v134, s[28:29]
	s_add_i32 m0, s25, 0x12000
	s_add_u32 s4, s28, 0x4000
	global_load_lds_dwordx4 v130, s[28:29]
	s_addc_u32 s5, s29, 0
	s_add_i32 m0, s25, 0x14000
	v_mov_b32_e32 v137, v139
	global_load_lds_dwordx4 v134, s[4:5]
	s_add_i32 m0, s25, 0x16000
	s_add_u32 s26, s76, s2
	s_addc_u32 s27, s33, s3
	s_add_i32 s40, s25, 0x2000
	global_load_lds_dwordx4 v130, s[4:5]
	s_mov_b32 m0, s25
	s_add_u32 s2, s26, 0x80000
	global_load_lds_dwordx4 v136, s[26:27]
	s_mov_b32 m0, s40
	s_addc_u32 s3, s27, 0
	s_add_i32 s41, s25, 0x4000
	global_load_lds_dwordx4 v132, s[26:27]
	s_mov_b32 m0, s41
	s_add_i32 s42, s25, 0x6000
	global_load_lds_dwordx4 v136, s[2:3]
	s_mov_b32 m0, s42
	v_mov_b32_e32 v133, v139
	global_load_lds_dwordx4 v132, s[2:3]
	s_cmp_eq_u32 s7, 1
	s_mov_b32 s43, 0
	v_mov_b32_e32 v135, v139
	v_mov_b32_e32 v131, v139
	s_mov_b64 s[4:5], 0x4000
	v_lshl_add_u64 v[2:3], s[26:27], 0, v[136:137]
	s_cselect_b64 s[2:3], -1, 0
	s_setprio 1
	s_cmp_lg_u32 s7, 1
	v_lshl_add_u64 v[4:5], s[26:27], 0, v[132:133]
	s_cbranch_scc1 .LBB0_1836
	s_setprio 0
	s_barrier

; template <class Epi, class Sched, bool ABLK = false, bool ALIGN_EPI = true, bool SP2 = true, bool BBLK = true>
; __device__ __forceinline__ void gemm_phase(LAS unsigned char* lds, const Gemm g, const Sched& S, const Epi& E) {
;     const int tid = tid_fresh(), wid = __builtin_amdgcn_readfirstlane(tid >> 6), lane = tid & 63, wr = wid >> 2, wc = wid & 3, fr = lane & 15, fq = lane >> 4;
;     unsigned voffA[2], voffB[2];
; #pragma unroll
;     for (int i = 0; i < 2; ++i) { int R, C; stage_rc(tid * 16 + i * 8192, R, C); const int r32 = Epi::PERM ? perm32(R & 31) : (R & 31);
;         const int Rb = Epi::ADJ ? 64 * (R >> 5) + r32 : (R & ~31) + r32;
;         voffA[i] = (unsigned)(R * (ABLK ? 64 : g.lda) + C) * 2u; voffB[i] = BBLK ? (unsigned)(R * 64 + C) * 2u : (unsigned)(Rb * g.ldb + C) * 2u; }
;     const size_t kstep = (size_t)(BK * 2);
;     const size_t hstepA = (size_t)HALF * (ABLK ? 64 : g.lda) * 2, hstepB = BBLK ? (size_t)16384 : (size_t)(Epi::ADJ ? 32 : HALF) * g.ldb * 2;
;     const size_t tstepB = BBLK ? ((size_t)g.ldb / 64) * 32768 : (size_t)BM * g.ldb * 2;
;     const size_t kstepB = BBLK ? (size_t)32768 : kstep;
;     auto b_k0 = [&](int k0) -> size_t { return BBLK ? (size_t)(k0 / BK) * 32768 : (size_t)k0 * 2; };
;     const unsigned ldsw = (unsigned)wid * 1024u;
;     const int aoff = lds_byte(wr * 64 + fr, fq * 8), boff = lds_byte(wc * 32 + fr, fq * 8);
;     ...
;     Unit cur, nxt; int ui = 0;
;     if (!S.next(0, cur)) return;
;     f32x4 acc[2][2][4][2];
; #pragma unroll
;     for (int a = 0; a < 2; ++a)
; #pragma unroll
;         for (int b = 0; b < 2; ++b)
; #pragma unroll
;             for (int m = 0; m < 4; ++m)
; #pragma unroll
;                 for (int n = 0; n < 2; ++n) acc[a][b][m][n] = (f32x4){0.f, 0.f, 0.f, 0.f};
;     bf16x8 At[4][2], B0[2][2], B1[2][2];
;     auto a_unit = [&](const Unit& u) -> const char* { return ABLK ? (const char*)g.A + (size_t)u.pm * ((size_t)g.lda / 64) * 32768 : (const char*)g.A + (size_t)u.pm * 2 * hstepA; };
;     auto a_tile = [&](const char* ub, int tau) -> const char* { return ub + (size_t)tau * (ABLK ? (size_t)32768 : kstep); };
;     const char* uA = a_unit(cur); int tbA = cur.k0 / BK;
;     const char* cA = a_tile(uA, tbA); const char* cB = (const char*)g.Bt + (size_t)cur.pn * tstepB + b_k0(cur.k0);
;     S.a_ready(cur);
;     if constexpr (SP2) {
.LBB0_1901:
	s_or_b64 exec, exec, s[2:3]
	v_mov_b32_e32 v4, v0
	s_waitcnt lgkmcnt(0)
	s_barrier
	s_add_u32 s1, s68, 0x12900000
	v_bfe_i32 v3, v4, 27, 1
	v_lshlrev_b32_e32 v1, 4, v4
	v_lshrrev_b32_e32 v3, 22, v3
	v_add_u32_e32 v3, v1, v3
	v_and_b32_e32 v3, 0xfffffc00, v3
	v_sub_u32_e32 v3, v1, v3
	v_lshrrev_b32_e32 v5, 4, v3
	v_bitop3_b32 v5, v5, v3, 32 bitop3:0x6c
	v_ashrrev_i32_e32 v3, 31, v3
	v_lshrrev_b32_e32 v3, 26, v3
	v_ashrrev_i32_e32 v2, 31, v4
	v_add_u32_e32 v3, v5, v3
	v_lshrrev_b32_e32 v2, 26, v2
	v_ashrrev_i32_e32 v3, 6, v3
	v_add_u32_e32 v2, v4, v2
	v_mul_i32_i24_e32 v8, 64, v3
	v_ashrrev_i32_e32 v2, 6, v2
	v_sub_u32_e32 v5, v5, v8
	v_mov_b32_e32 v8, 1
	v_lshlrev_b32_e32 v6, 3, v2
	v_lshlrev_b32_e32 v7, 5, v2
	v_ashrrev_i16_sdwa v5, v8, sext(v5) dst_sel:DWORD dst_unused:UNUSED_PAD src0_sel:DWORD src1_sel:BYTE_0
	v_and_b32_e32 v6, 0x1fffff0, v6
	v_and_b32_e32 v7, 32, v7
	v_bfe_i32 v5, v5, 0, 16
	v_add_u32_e32 v7, v7, v5
	v_add_lshl_u32 v6, v3, v6, 7
	v_add_u32_e32 v1, 0x2000, v1
	v_lshl_add_u32 v130, v7, 1, v6
	v_ashrrev_i32_e32 v6, 31, v1
	v_lshrrev_b32_e32 v6, 22, v6
	v_add_u32_e32 v6, v1, v6
	v_ashrrev_i32_e32 v6, 10, v6
	v_mul_i32_i24_e32 v7, 0x400, v6
	v_sub_u32_e32 v1, v1, v7
	v_lshrrev_b32_e32 v7, 4, v1
	v_bitop3_b32 v1, v7, v1, 32 bitop3:0x6c
	v_lshlrev_b32_e32 v7, 3, v6
	v_and_b32_e32 v9, 0x1fffff0, v7
	v_ashrrev_i32_e32 v7, 31, v1
	v_readfirstlane_b32 s4, v4
	v_lshrrev_b32_e32 v7, 26, v7
	s_addc_u32 s33, s69, 0
	s_ashr_i32 s5, s4, 6
	v_add_u32_e32 v10, v1, v7
	v_ashrrev_i32_e32 v7, 6, v10
	v_and_b32_e32 v10, 0xc0, v10
	s_ashr_i32 s6, s4, 8
	s_lshl_b32 s40, s5, 10
	v_readlane_b32 s2, v252, 16
	v_sub_u32_e32 v1, v1, v10
	s_add_u32 s30, s1, s2
	v_lshlrev_b32_e32 v11, 5, v6
	v_ashrrev_i16_sdwa v1, v8, sext(v1) dst_sel:DWORD dst_unused:UNUSED_PAD src0_sel:DWORD src1_sel:BYTE_0
	s_addc_u32 s31, s33, 0
	s_add_i32 s41, s40, 0
	v_and_b32_e32 v11, 32, v11
	v_bfe_i32 v8, v1, 0, 16
	s_add_i32 m0, s41, 0x10000
	v_add_u32_e32 v1, v11, v8
	v_add_lshl_u32 v9, v7, v9, 7
	global_load_lds_dwordx4 v130, s[30:31]
	s_add_i32 m0, s41, 0x12000
	v_lshl_add_u32 v132, v1, 1, v9
	s_add_u32 s2, s30, 0x4000
	global_load_lds_dwordx4 v132, s[30:31]
	s_addc_u32 s3, s31, 0
	s_add_i32 m0, s41, 0x14000
	v_mov_b32_e32 v131, 0
	global_load_lds_dwordx4 v130, s[2:3]
	s_add_i32 m0, s41, 0x16000
	s_mov_b32 s47, 0
	global_load_lds_dwordx4 v132, s[2:3]
	v_readlane_b32 s2, v252, 17
	v_readlane_b32 s3, v252, 18
	s_add_u32 s34, s62, s2
	s_addc_u32 s35, s83, s3
	s_add_i32 s42, s41, 0x2000
	s_mov_b32 m0, s41
	s_add_u32 s2, s34, 0x4000
	global_load_lds_dwordx4 v130, s[34:35]
	s_mov_b32 m0, s42
	s_addc_u32 s3, s35, 0
	s_add_i32 s43, s41, 0x4000
	global_load_lds_dwordx4 v132, s[34:35]
	s_mov_b32 m0, s43
	s_add_i32 s44, s41, 0x6000
	global_load_lds_dwordx4 v130, s[2:3]
	s_mov_b32 m0, s44
	s_cmp_eq_u32 s6, 1
	global_load_lds_dwordx4 v132, s[2:3]
	s_cselect_b64 s[2:3], -1, 0
	s_setprio 1
	s_cmp_lg_u32 s6, 1
	v_mov_b32_e32 v133, v131
	s_cbranch_scc1 .LBB0_1903
	s_setprio 0
	s_barrier

; template <class Epi, class Sched, bool ABLK = false, bool ALIGN_EPI = true, bool SP2 = true, bool BBLK = true>
; __device__ __forceinline__ void gemm_phase(LAS unsigned char* lds, const Gemm g, const Sched& S, const Epi& E) {
;     const int tid = tid_fresh(), wid = __builtin_amdgcn_readfirstlane(tid >> 6), lane = tid & 63, wr = wid >> 2, wc = wid & 3, fr = lane & 15, fq = lane >> 4;
;     unsigned voffA[2], voffB[2];
; #pragma unroll
;     for (int i = 0; i < 2; ++i) { int R, C; stage_rc(tid * 16 + i * 8192, R, C); const int r32 = Epi::PERM ? perm32(R & 31) : (R & 31);
;         const int Rb = Epi::ADJ ? 64 * (R >> 5) + r32 : (R & ~31) + r32;
;         voffA[i] = (unsigned)(R * (ABLK ? 64 : g.lda) + C) * 2u; voffB[i] = BBLK ? (unsigned)(R * 64 + C) * 2u : (unsigned)(Rb * g.ldb + C) * 2u; }
;     const size_t kstep = (size_t)(BK * 2);
;     const size_t hstepA = (size_t)HALF * (ABLK ? 64 : g.lda) * 2, hstepB = BBLK ? (size_t)16384 : (size_t)(Epi::ADJ ? 32 : HALF) * g.ldb * 2;
;     const size_t tstepB = BBLK ? ((size_t)g.ldb / 64) * 32768 : (size_t)BM * g.ldb * 2;
;     const size_t kstepB = BBLK ? (size_t)32768 : kstep;
;     auto b_k0 = [&](int k0) -> size_t { return BBLK ? (size_t)(k0 / BK) * 32768 : (size_t)k0 * 2; };
;     const unsigned ldsw = (unsigned)wid * 1024u;
;     const int aoff = lds_byte(wr * 64 + fr, fq * 8), boff = lds_byte(wc * 32 + fr, fq * 8);
;     ...
;     Unit cur, nxt; int ui = 0;
;     if (!S.next(0, cur)) return;
;     f32x4 acc[2][2][4][2];
; #pragma unroll
;     for (int a = 0; a < 2; ++a)
; #pragma unroll
;         for (int b = 0; b < 2; ++b)
; #pragma unroll
;             for (int m = 0; m < 4; ++m)
; #pragma unroll
;                 for (int n = 0; n < 2; ++n) acc[a][b][m][n] = (f32x4){0.f, 0.f, 0.f, 0.f};
;     bf16x8 At[4][2], B0[2][2], B1[2][2];
;     auto a_unit = [&](const Unit& u) -> const char* { return ABLK ? (const char*)g.A + (size_t)u.pm * ((size_t)g.lda / 64) * 32768 : (const char*)g.A + (size_t)u.pm * 2 * hstepA; };
;     auto a_tile = [&](const char* ub, int tau) -> const char* { return ub + (size_t)tau * (ABLK ? (size_t)32768 : kstep); };
;     const char* uA = a_unit(cur); int tbA = cur.k0 / BK;
;     const char* cA = a_tile(uA, tbA); const char* cB = (const char*)g.Bt + (size_t)cur.pn * tstepB + b_k0(cur.k0);
;     S.a_ready(cur);
;     if constexpr (SP2) {
.LBB0_2129:
	s_or_b64 exec, exec, s[2:3]
	v_readlane_b32 s2, v252, 12
	s_add_u32 s8, s68, 0x1e100000
	v_mov_b32_e32 v6, v0
	v_readlane_b32 s3, v252, 13
	s_addc_u32 s9, s69, 0
	s_waitcnt lgkmcnt(0)
	s_barrier
	s_andn2_b64 vcc, exec, s[2:3]
	v_readfirstlane_b32 s4, v6
	s_cbranch_vccnz .LBB0_2145
	v_lshlrev_b32_e32 v1, 4, v6
	v_add_u32_e32 v2, 0x2000, v1
	v_ashrrev_i32_e32 v3, 31, v2
	v_lshrrev_b32_e32 v3, 22, v3
	v_add_u32_e32 v3, v2, v3
	v_ashrrev_i32_e32 v7, 10, v3
	v_mul_i32_i24_e32 v4, 0x400, v7
	v_sub_u32_e32 v2, v2, v4
	v_lshrrev_b32_e32 v4, 4, v2
	v_bitop3_b32 v2, v4, v2, 32 bitop3:0x6c
	v_ashrrev_i32_e32 v4, 31, v2
	v_lshrrev_b32_e32 v4, 26, v4
	v_add_u32_e32 v4, v2, v4
	v_ashrrev_i32_e32 v8, 6, v4
	v_and_b32_e32 v4, 0xc0, v4
	v_sub_u32_e32 v2, v2, v4
	v_mov_b32_e32 v4, 1
	v_lshlrev_b32_e32 v3, 5, v7
	v_ashrrev_i16_sdwa v2, v4, sext(v2) dst_sel:DWORD dst_unused:UNUSED_PAD src0_sel:DWORD src1_sel:BYTE_0
	v_and_b32_e32 v3, 32, v3
	v_bfe_i32 v9, v2, 0, 16
	v_add_u32_e32 v2, v3, v9
	v_lshlrev_b32_e32 v3, 3, v7
	v_and_b32_e32 v3, -16, v3
	v_add_u32_e32 v3, v8, v3
	v_lshlrev_b32_e32 v5, 7, v3
	v_lshl_add_u32 v130, v2, 1, v5
	s_movk_i32 s7, 0xf80
	v_mad_u64_u32 v[132:133], s[2:3], v3, s7, v[130:131]
	v_bfe_i32 v3, v6, 27, 1
	v_lshrrev_b32_e32 v3, 22, v3
	v_add_u32_e32 v3, v1, v3
	v_and_b32_e32 v3, 0xfffffc00, v3
	v_sub_u32_e32 v1, v1, v3
	v_lshrrev_b32_e32 v3, 4, v1
	v_bitop3_b32 v3, v3, v1, 32 bitop3:0x6c
	v_ashrrev_i32_e32 v1, 31, v1
	v_lshrrev_b32_e32 v1, 26, v1
	v_ashrrev_i32_e32 v2, 31, v6
	v_add_u32_e32 v1, v3, v1
	v_lshrrev_b32_e32 v2, 26, v2
	v_ashrrev_i32_e32 v11, 6, v1
	v_add_u32_e32 v2, v6, v2
	v_mul_i32_i24_e32 v1, 64, v11
	v_ashrrev_i32_e32 v10, 6, v2
	v_sub_u32_e32 v1, v3, v1
	v_lshlrev_b32_e32 v2, 5, v10
	v_ashrrev_i16_sdwa v1, v4, sext(v1) dst_sel:DWORD dst_unused:UNUSED_PAD src0_sel:DWORD src1_sel:BYTE_0
	v_and_b32_e32 v2, 32, v2
	v_bfe_i32 v12, v1, 0, 16
	v_add_u32_e32 v1, v2, v12
	v_lshlrev_b32_e32 v2, 3, v10
	v_and_b32_e32 v2, -16, v2
	s_add_u32 s1, s68, 0x1100000
	v_add_u32_e32 v2, v11, v2
	s_addc_u32 s33, s69, 0
	s_ashr_i32 s6, s4, 6
	v_lshlrev_b32_e32 v3, 7, v2
	s_ashr_i32 s5, s4, 8
	s_lshl_b32 s36, s6, 10
	v_lshl_add_u32 v134, v1, 1, v3
	s_add_u32 s37, s68, 0x2d100000
	v_mad_u64_u32 v[136:137], s[2:3], v2, s7, v[134:135]
	s_addc_u32 s38, s69, 0
	s_lshr_b32 s2, s70, 31
	s_add_i32 s2, s70, s2
	s_ashr_i32 s20, s2, 1
	s_sub_i32 s2, s63, s20
	s_lshl_b32 s2, s2, 1
	s_add_i32 s22, s2, s70
	s_ashr_i32 s21, s20, 31
	s_ashr_i32 s23, s22, 31
	s_lshl_b64 s[2:3], s[20:21], 20
	s_lshl_b64 s[10:11], s[22:23], 20
	s_add_u32 s26, s1, s10
	s_addc_u32 s27, s33, s11
	s_add_i32 s21, s36, 0
	s_add_i32 m0, s21, 0x10000
	v_mov_b32_e32 v135, 0
	global_load_lds_dwordx4 v134, s[26:27]
	s_add_i32 m0, s21, 0x12000
	s_add_u32 s10, s26, 0x4000
	global_load_lds_dwordx4 v130, s[26:27]
	s_addc_u32 s11, s27, 0
	s_add_i32 m0, s21, 0x14000
	v_mov_b32_e32 v137, v135
	global_load_lds_dwordx4 v134, s[10:11]
	s_add_i32 m0, s21, 0x16000
	s_add_u32 s24, s37, s2
	s_addc_u32 s25, s38, s3
	s_add_i32 s23, s21, 0x2000
	global_load_lds_dwordx4 v130, s[10:11]
	s_mov_b32 m0, s21
	s_add_u32 s2, s24, 0x80000
	global_load_lds_dwordx4 v136, s[24:25]
	s_mov_b32 m0, s23
	s_addc_u32 s3, s25, 0
	s_add_i32 s39, s21, 0x4000
	global_load_lds_dwordx4 v132, s[24:25]
	s_mov_b32 m0, s39
	s_add_i32 s40, s21, 0x6000
	global_load_lds_dwordx4 v136, s[2:3]
	s_mov_b32 m0, s40
	v_mov_b32_e32 v133, v135
	global_load_lds_dwordx4 v132, s[2:3]
	s_cmp_eq_u32 s5, 1
	s_mov_b32 s41, 0
	v_mov_b32_e32 v131, v135
	v_lshl_add_u64 v[2:3], s[24:25], 0, v[136:137]
	s_cselect_b64 s[2:3], -1, 0
	s_setprio 1
	s_cmp_lg_u32 s5, 1
	v_lshl_add_u64 v[4:5], s[24:25], 0, v[132:133]
	s_cbranch_scc1 .LBB0_2132
	s_setprio 0
	s_barrier

; template <class Epi, class Sched, bool ABLK = false, bool ALIGN_EPI = true, bool SP2 = true, bool BBLK = true>
; __device__ __forceinline__ void gemm_phase(LAS unsigned char* lds, const Gemm g, const Sched& S, const Epi& E) {
;     const int tid = tid_fresh(), wid = __builtin_amdgcn_readfirstlane(tid >> 6), lane = tid & 63, wr = wid >> 2, wc = wid & 3, fr = lane & 15, fq = lane >> 4;
;     unsigned voffA[2], voffB[2];
; #pragma unroll
;     for (int i = 0; i < 2; ++i) { int R, C; stage_rc(tid * 16 + i * 8192, R, C); const int r32 = Epi::PERM ? perm32(R & 31) : (R & 31);
;         const int Rb = Epi::ADJ ? 64 * (R >> 5) + r32 : (R & ~31) + r32;
;         voffA[i] = (unsigned)(R * (ABLK ? 64 : g.lda) + C) * 2u; voffB[i] = BBLK ? (unsigned)(R * 64 + C) * 2u : (unsigned)(Rb * g.ldb + C) * 2u; }
;     const size_t kstep = (size_t)(BK * 2);
;     const size_t hstepA = (size_t)HALF * (ABLK ? 64 : g.lda) * 2, hstepB = BBLK ? (size_t)16384 : (size_t)(Epi::ADJ ? 32 : HALF) * g.ldb * 2;
;     const size_t tstepB = BBLK ? ((size_t)g.ldb / 64) * 32768 : (size_t)BM * g.ldb * 2;
;     const size_t kstepB = BBLK ? (size_t)32768 : kstep;
;     auto b_k0 = [&](int k0) -> size_t { return BBLK ? (size_t)(k0 / BK) * 32768 : (size_t)k0 * 2; };
;     const unsigned ldsw = (unsigned)wid * 1024u;
;     const int aoff = lds_byte(wr * 64 + fr, fq * 8), boff = lds_byte(wc * 32 + fr, fq * 8);
;     ...
;     Unit cur, nxt; int ui = 0;
;     if (!S.next(0, cur)) return;
;     f32x4 acc[2][2][4][2];
; #pragma unroll
;     for (int a = 0; a < 2; ++a)
; #pragma unroll
;         for (int b = 0; b < 2; ++b)
; #pragma unroll
;             for (int m = 0; m < 4; ++m)
; #pragma unroll
;                 for (int n = 0; n < 2; ++n) acc[a][b][m][n] = (f32x4){0.f, 0.f, 0.f, 0.f};
;     bf16x8 At[4][2], B0[2][2], B1[2][2];
;     auto a_unit = [&](const Unit& u) -> const char* { return ABLK ? (const char*)g.A + (size_t)u.pm * ((size_t)g.lda / 64) * 32768 : (const char*)g.A + (size_t)u.pm * 2 * hstepA; };
;     auto a_tile = [&](const char* ub, int tau) -> const char* { return ub + (size_t)tau * (ABLK ? (size_t)32768 : kstep); };
;     const char* uA = a_unit(cur); int tbA = cur.k0 / BK;
;     const char* cA = a_tile(uA, tbA); const char* cB = (const char*)g.Bt + (size_t)cur.pn * tstepB + b_k0(cur.k0);
;     S.a_ready(cur);
;     if constexpr (SP2) {
.LBB0_2254:
	s_or_b64 exec, exec, s[2:3]
	v_readlane_b32 s2, v252, 26
	s_add_u32 s1, s68, 0x23100000
	s_waitcnt lgkmcnt(0)
	v_mov_b32_e32 v1, v0
	v_readlane_b32 s3, v252, 27
	s_addc_u32 s33, s69, 0
	s_barrier
	s_and_b64 vcc, exec, s[2:3]
	v_readfirstlane_b32 s2, v1
	s_cbranch_vccnz .LBB0_2270
	v_lshlrev_b32_e32 v2, 4, v1
	v_add_u32_e32 v3, 0x2000, v2
	v_ashrrev_i32_e32 v4, 31, v3
	v_lshrrev_b32_e32 v4, 22, v4
	v_add_u32_e32 v4, v3, v4
	v_ashrrev_i32_e32 v6, 10, v4
	v_mul_i32_i24_e32 v5, 0x400, v6
	v_sub_u32_e32 v3, v3, v5
	v_lshrrev_b32_e32 v5, 4, v3
	v_bitop3_b32 v3, v5, v3, 32 bitop3:0x6c
	v_ashrrev_i32_e32 v5, 31, v3
	v_lshrrev_b32_e32 v5, 26, v5
	v_add_u32_e32 v5, v3, v5
	v_ashrrev_i32_e32 v7, 6, v5
	v_and_b32_e32 v5, 0xc0, v5
	v_sub_u32_e32 v3, v3, v5
	v_mov_b32_e32 v5, 1
	v_lshlrev_b32_e32 v4, 5, v6
	v_ashrrev_i16_sdwa v3, v5, sext(v3) dst_sel:DWORD dst_unused:UNUSED_PAD src0_sel:DWORD src1_sel:BYTE_0
	v_and_b32_e32 v4, 32, v4
	v_bfe_i32 v8, v3, 0, 16
	v_add_u32_e32 v3, v4, v8
	v_lshlrev_b32_e32 v4, 3, v6
	v_and_b32_e32 v4, -16, v4
	v_add_u32_e32 v4, v7, v4
	v_lshlrev_b32_e32 v9, 7, v4
	v_lshl_add_u32 v130, v3, 1, v9
	s_movk_i32 s6, 0xf80
	v_mad_u64_u32 v[132:133], s[4:5], v4, s6, v[130:131]
	v_bfe_i32 v4, v1, 27, 1
	v_lshrrev_b32_e32 v4, 22, v4
	v_add_u32_e32 v4, v2, v4
	v_and_b32_e32 v4, 0xfffffc00, v4
	v_sub_u32_e32 v2, v2, v4
	v_lshrrev_b32_e32 v4, 4, v2
	v_bitop3_b32 v4, v4, v2, 32 bitop3:0x6c
	v_ashrrev_i32_e32 v2, 31, v2
	v_lshrrev_b32_e32 v2, 26, v2
	v_ashrrev_i32_e32 v3, 31, v1
	v_add_u32_e32 v2, v4, v2
	v_lshrrev_b32_e32 v3, 26, v3
	v_ashrrev_i32_e32 v10, 6, v2
	v_add_u32_e32 v3, v1, v3
	v_mul_i32_i24_e32 v2, 64, v10
	v_ashrrev_i32_e32 v9, 6, v3
	v_sub_u32_e32 v2, v4, v2
	v_lshlrev_b32_e32 v3, 5, v9
	v_ashrrev_i16_sdwa v2, v5, sext(v2) dst_sel:DWORD dst_unused:UNUSED_PAD src0_sel:DWORD src1_sel:BYTE_0
	v_and_b32_e32 v3, 32, v3
	v_bfe_i32 v11, v2, 0, 16
	v_add_u32_e32 v2, v3, v11
	v_lshlrev_b32_e32 v3, 3, v9
	v_and_b32_e32 v3, -16, v3
	s_add_u32 s38, s68, 0xc900000
	v_add_u32_e32 v3, v10, v3
	s_addc_u32 s39, s69, 0
	s_ashr_i32 s10, s2, 6
	v_lshlrev_b32_e32 v4, 7, v3
	s_ashr_i32 s3, s2, 8
	s_lshl_b32 s40, s10, 10
	v_lshl_add_u32 v134, v2, 1, v4
	s_add_u32 s41, s68, 0x1b900000
	v_mad_u64_u32 v[136:137], s[4:5], v3, s6, v[134:135]
	s_addc_u32 s42, s69, 0
	s_lshr_b32 s4, s70, 30
	s_add_i32 s4, s70, s4
	s_ashr_i32 s22, s4, 2
	s_sub_i32 s4, s63, s22
	s_lshl_b32 s4, s4, 2
	s_add_i32 s24, s4, s70
	s_ashr_i32 s23, s22, 31
	s_ashr_i32 s25, s24, 31
	s_lshl_b64 s[4:5], s[22:23], 20
	s_lshl_b64 s[6:7], s[24:25], 20
	s_add_u32 s28, s38, s6
	s_addc_u32 s29, s39, s7
	s_add_i32 s25, s40, 0
	s_add_i32 m0, s25, 0x10000
	v_mov_b32_e32 v139, 0
	global_load_lds_dwordx4 v134, s[28:29]
	s_add_i32 m0, s25, 0x12000
	s_add_u32 s6, s28, 0x4000
	global_load_lds_dwordx4 v130, s[28:29]
	s_addc_u32 s7, s29, 0
	s_add_i32 m0, s25, 0x14000
	v_mov_b32_e32 v137, v139
	global_load_lds_dwordx4 v134, s[6:7]
	s_add_i32 m0, s25, 0x16000
	s_add_u32 s26, s41, s4
	s_addc_u32 s27, s42, s5
	s_add_i32 s43, s25, 0x2000
	global_load_lds_dwordx4 v130, s[6:7]
	s_mov_b32 m0, s25
	s_add_u32 s4, s26, 0x80000
	global_load_lds_dwordx4 v136, s[26:27]
	s_mov_b32 m0, s43
	s_addc_u32 s5, s27, 0
	s_add_i32 s44, s25, 0x4000
	global_load_lds_dwordx4 v132, s[26:27]
	s_mov_b32 m0, s44
	s_add_i32 s45, s25, 0x6000
	global_load_lds_dwordx4 v136, s[4:5]
	s_mov_b32 m0, s45
	v_mov_b32_e32 v133, v139
	global_load_lds_dwordx4 v132, s[4:5]
	s_cmp_eq_u32 s3, 1
	s_mov_b32 s46, 0
	v_mov_b32_e32 v135, v139
	v_mov_b32_e32 v131, v139
	s_mov_b64 s[4:5], 0x4000
	v_lshl_add_u64 v[2:3], s[26:27], 0, v[136:137]
	s_cselect_b64 s[6:7], -1, 0
	s_setprio 1
	s_cmp_lg_u32 s3, 1
	v_lshl_add_u64 v[4:5], s[26:27], 0, v[132:133]
	s_cbranch_scc1 .LBB0_2257
	s_setprio 0
	s_barrier

; template <class Epi, class Sched, bool ABLK = false, bool ALIGN_EPI = true, bool SP2 = true, bool BBLK = true>
; __device__ __forceinline__ void gemm_phase(LAS unsigned char* lds, const Gemm g, const Sched& S, const Epi& E) {
;     const int tid = tid_fresh(), wid = __builtin_amdgcn_readfirstlane(tid >> 6), lane = tid & 63, wr = wid >> 2, wc = wid & 3, fr = lane & 15, fq = lane >> 4;
;     unsigned voffA[2], voffB[2];
; #pragma unroll
;     for (int i = 0; i < 2; ++i) { int R, C; stage_rc(tid * 16 + i * 8192, R, C); const int r32 = Epi::PERM ? perm32(R & 31) : (R & 31);
;         const int Rb = Epi::ADJ ? 64 * (R >> 5) + r32 : (R & ~31) + r32;
;         voffA[i] = (unsigned)(R * (ABLK ? 64 : g.lda) + C) * 2u; voffB[i] = BBLK ? (unsigned)(R * 64 + C) * 2u : (unsigned)(Rb * g.ldb + C) * 2u; }
;     const size_t kstep = (size_t)(BK * 2);
;     const size_t hstepA = (size_t)HALF * (ABLK ? 64 : g.lda) * 2, hstepB = BBLK ? (size_t)16384 : (size_t)(Epi::ADJ ? 32 : HALF) * g.ldb * 2;
;     const size_t tstepB = BBLK ? ((size_t)g.ldb / 64) * 32768 : (size_t)BM * g.ldb * 2;
;     const size_t kstepB = BBLK ? (size_t)32768 : kstep;
;     auto b_k0 = [&](int k0) -> size_t { return BBLK ? (size_t)(k0 / BK) * 32768 : (size_t)k0 * 2; };
;     const unsigned ldsw = (unsigned)wid * 1024u;
;     const int aoff = lds_byte(wr * 64 + fr, fq * 8), boff = lds_byte(wc * 32 + fr, fq * 8);
;     ...
;     Unit cur, nxt; int ui = 0;
;     if (!S.next(0, cur)) return;
;     f32x4 acc[2][2][4][2];
; #pragma unroll
;     for (int a = 0; a < 2; ++a)
; #pragma unroll
;         for (int b = 0; b < 2; ++b)
; #pragma unroll
;             for (int m = 0; m < 4; ++m)
; #pragma unroll
;                 for (int n = 0; n < 2; ++n) acc[a][b][m][n] = (f32x4){0.f, 0.f, 0.f, 0.f};
;     bf16x8 At[4][2], B0[2][2], B1[2][2];
;     auto a_unit = [&](const Unit& u) -> const char* { return ABLK ? (const char*)g.A + (size_t)u.pm * ((size_t)g.lda / 64) * 32768 : (const char*)g.A + (size_t)u.pm * 2 * hstepA; };
;     auto a_tile = [&](const char* ub, int tau) -> const char* { return ub + (size_t)tau * (ABLK ? (size_t)32768 : kstep); };
;     const char* uA = a_unit(cur); int tbA = cur.k0 / BK;
;     const char* cA = a_tile(uA, tbA); const char* cB = (const char*)g.Bt + (size_t)cur.pn * tstepB + b_k0(cur.k0);
;     S.a_ready(cur);
;     if constexpr (SP2) {
.LBB0_2322:
	s_or_b64 exec, exec, s[2:3]
	v_mov_b32_e32 v4, v0
	s_waitcnt lgkmcnt(0)
	s_barrier
	s_add_u32 s46, s68, 0x14900000
	v_bfe_i32 v3, v4, 27, 1
	v_lshlrev_b32_e32 v1, 4, v4
	v_lshrrev_b32_e32 v3, 22, v3
	v_add_u32_e32 v3, v1, v3
	v_and_b32_e32 v3, 0xfffffc00, v3
	v_sub_u32_e32 v3, v1, v3
	v_lshrrev_b32_e32 v5, 4, v3
	v_bitop3_b32 v5, v5, v3, 32 bitop3:0x6c
	v_ashrrev_i32_e32 v3, 31, v3
	v_lshrrev_b32_e32 v3, 26, v3
	v_ashrrev_i32_e32 v2, 31, v4
	v_add_u32_e32 v3, v5, v3
	v_lshrrev_b32_e32 v2, 26, v2
	v_ashrrev_i32_e32 v3, 6, v3
	v_add_u32_e32 v2, v4, v2
	v_mul_i32_i24_e32 v8, 64, v3
	v_ashrrev_i32_e32 v2, 6, v2
	v_sub_u32_e32 v5, v5, v8
	v_mov_b32_e32 v8, 1
	v_lshlrev_b32_e32 v6, 3, v2
	v_lshlrev_b32_e32 v7, 5, v2
	v_ashrrev_i16_sdwa v5, v8, sext(v5) dst_sel:DWORD dst_unused:UNUSED_PAD src0_sel:DWORD src1_sel:BYTE_0
	v_and_b32_e32 v6, 0x1fffff0, v6
	v_and_b32_e32 v7, 32, v7
	v_bfe_i32 v5, v5, 0, 16
	v_add_u32_e32 v7, v7, v5
	v_add_lshl_u32 v6, v3, v6, 7
	v_add_u32_e32 v1, 0x2000, v1
	v_lshl_add_u32 v130, v7, 1, v6
	v_ashrrev_i32_e32 v6, 31, v1
	v_lshrrev_b32_e32 v6, 22, v6
	v_add_u32_e32 v6, v1, v6
	v_ashrrev_i32_e32 v6, 10, v6
	v_mul_i32_i24_e32 v7, 0x400, v6
	v_sub_u32_e32 v1, v1, v7
	v_lshrrev_b32_e32 v7, 4, v1
	v_bitop3_b32 v1, v7, v1, 32 bitop3:0x6c
	v_lshlrev_b32_e32 v7, 3, v6
	v_and_b32_e32 v9, 0x1fffff0, v7
	v_ashrrev_i32_e32 v7, 31, v1
	v_readfirstlane_b32 s2, v4
	v_lshrrev_b32_e32 v7, 26, v7
	s_addc_u32 s47, s69, 0
	s_ashr_i32 s4, s2, 6
	v_add_u32_e32 v10, v1, v7
	v_ashrrev_i32_e32 v7, 6, v10
	v_and_b32_e32 v10, 0xc0, v10
	s_ashr_i32 s3, s2, 8
	s_lshl_b32 s48, s4, 10
	v_readlane_b32 s5, v252, 16
	v_sub_u32_e32 v1, v1, v10
	s_add_u32 s38, s46, s5
	v_lshlrev_b32_e32 v11, 5, v6
	v_ashrrev_i16_sdwa v1, v8, sext(v1) dst_sel:DWORD dst_unused:UNUSED_PAD src0_sel:DWORD src1_sel:BYTE_0
	s_addc_u32 s39, s47, 0
	s_add_i32 s49, s48, 0
	v_and_b32_e32 v11, 32, v11
	v_bfe_i32 v8, v1, 0, 16
	s_add_i32 m0, s49, 0x10000
	v_add_u32_e32 v1, v11, v8
	v_add_lshl_u32 v9, v7, v9, 7
	global_load_lds_dwordx4 v130, s[38:39]
	s_add_i32 m0, s49, 0x12000
	v_lshl_add_u32 v132, v1, 1, v9
	s_add_u32 s6, s38, 0x4000
	global_load_lds_dwordx4 v132, s[38:39]
	s_addc_u32 s7, s39, 0
	s_add_i32 m0, s49, 0x14000
	v_mov_b32_e32 v131, 0
	global_load_lds_dwordx4 v130, s[6:7]
	s_add_i32 m0, s49, 0x16000
	s_mov_b32 s55, 0
	global_load_lds_dwordx4 v132, s[6:7]
	v_readlane_b32 s6, v252, 17
	v_readlane_b32 s7, v252, 18
	s_add_u32 s40, s1, s6
	s_addc_u32 s41, s33, s7
	s_add_i32 s50, s49, 0x2000
	s_mov_b32 m0, s49
	s_add_u32 s6, s40, 0x4000
	global_load_lds_dwordx4 v130, s[40:41]
	s_mov_b32 m0, s50
	s_addc_u32 s7, s41, 0
	s_add_i32 s51, s49, 0x4000
	global_load_lds_dwordx4 v132, s[40:41]
	s_mov_b32 m0, s51
	s_add_i32 s52, s49, 0x6000
	global_load_lds_dwordx4 v130, s[6:7]
	s_mov_b32 m0, s52
	s_cmp_eq_u32 s3, 1
	global_load_lds_dwordx4 v132, s[6:7]
	s_cselect_b64 s[10:11], -1, 0
	s_setprio 1
	s_cmp_lg_u32 s3, 1
	v_mov_b32_e32 v133, v131
	s_cbranch_scc1 .LBB0_2324
	s_setprio 0
	s_barrier
